# hoist rowss/sw scalar loads out of QKV, UV, FT epilogue row-group loops (1 wait instead of 8)
# speedup vs baseline: 1.0034x; 1.0034x over previous
; __device__ __forceinline__ unsigned pk2(float lo, float hi) { unsigned r; asm volatile("v_cvt_pk_bf16_f32 %0, %1, %2" : "=v"(r) : "v"(lo), "v"(hi)); return r; }
; __device__ __forceinline__ float rstd_of(float ss) { return __builtin_amdgcn_rsqf(ss * (1.0f / 1024.0f) + EPS); }
;     __device__ __forceinline__ void operator()(const f32x4 (&acc)[2][2][4][2], const Unit& u, int wr, int wc, int fr_, int fq_) const {
;     ...
;         const int mb = mb_of_panel(u.pm), lr0 = wr * 64 + fr, col0 = u.pn * 256 + wc * 32 + 4 * fq;
;         f32x4 bv[2][2];
; #pragma unroll
;         for (int bj = 0; bj < 2; ++bj)
; #pragma unroll
;             for (int n = 0; n < 2; ++n) bv[bj][n] = *(const f32x4*)(sw + (size_t)mb * NGU + col0 + bj * 128 + n * 16);
; #pragma unroll
;         for (int ai = 0; ai < 2; ++ai)
; #pragma unroll
;             for (int m = 0; m < 4; ++m) {
;                 const int lr = lr0 + ai * 128 + m * 16, r = u.pm * 256 + lr; const float rs = rstd_of(rowss[r]);
; #pragma unroll
;                 for (int bj = 0; bj < 2; ++bj)
; #pragma unroll
;                     for (int n = 0; n < 2; ++n) {
;                         const f32x4 v = acc[ai][bj][m][n] * rs + bv[bj][n];
;                         if (u.pn < 5) { u32x2 w; w.x = pk2(v[0], v[1]); w.y = pk2(v[2], v[3]); *(u32x2*)(qk + (size_t)r * 1280 + col0 + bj * 128 + n * 16) = w; }
;                         else { const int d = wc * 32 + 16 * n + 4 * fq; int b, key;
;                             if (u.pm < 128) { b = u.pm >> 4; key = (u.pm & 15) * 256 + lr; } else { b = u.pm - 128; key = SEQ + lr; }
;                             u32x2 w; w.x = pk2(v[0], v[1]); w.y = pk2(v[2], v[3]);
;                             *(u32x2*)(vb + ((size_t)(b * 2 + bj) * KEYS + key) * 128 + d) = w; }
.LBB0_197:
	s_min_i32 s2, s40, 0x80
	s_ashr_i32 s2, s2, 4
	s_lshl_b32 s3, s82, 8
	s_or_b32 s3, s3, s74
	s_mul_hi_i32 s29, s2, 0x5800
	s_mulk_i32 s2, 0x5800
	v_mov_b32_e32 v52, v211
	s_add_u32 s28, s51, s2
	s_addc_u32 s29, s54, s29
	v_and_or_b32 v164, v52, 15, s72
	s_lshl_b32 s86, s40, 8
	v_add_u32_e32 v158, s86, v164
	v_ashrrev_i32_e32 v159, 31, v158
	v_lshl_add_u64 v[154:155], v[158:159], 2, s[62:63]
	global_load_dword v156, v[154:155], off
	global_load_dword v172, v[154:155], off offset:64
	global_load_dword v173, v[154:155], off offset:128
	global_load_dword v174, v[154:155], off offset:192
	global_load_dword v175, v[154:155], off offset:512
	global_load_dword v176, v[154:155], off offset:576
	global_load_dword v177, v[154:155], off offset:640
	global_load_dword v178, v[154:155], off offset:704
	v_lshrrev_b32_e32 v53, 2, v52
	v_and_b32_e32 v157, 12, v53
	v_or_b32_e32 v152, s3, v157
	v_ashrrev_i32_e32 v153, 31, v152
	v_lshl_add_u64 v[52:53], v[152:153], 2, s[28:29]
	global_load_dwordx4 v[76:79], v[52:53], off
	global_load_dwordx4 v[68:71], v[52:53], off offset:64
	global_load_dwordx4 v[60:63], v[52:53], off offset:512
	s_nop 0
	global_load_dwordx4 v[52:55], v[52:53], off offset:576
	s_cmp_gt_i32 s82, 4
	v_or_b32_e32 v157, s74, v157
	s_cselect_b64 s[46:47], -1, 0
	s_cmpk_lt_i32 s40, 0x80
	s_mov_b64 s[84:85], -1
	v_lshlrev_b32_e32 v208, 1, v157
	s_cselect_b64 s[82:83], -1, 0
	s_add_i32 s2, s40, 0xffffff80
	s_ashr_i32 s69, s40, 4
	s_and_b32 s77, s86, 0xf00
	s_and_b64 vcc, exec, s[46:47]
	s_brev_b32 s44, 60
	s_waitcnt vmcnt(0)
	v_fmamk_f32 v156, v156, 0x3a800000, v213
	v_rsq_f32_e32 v156, v156
	s_nop 0
	v_pk_fma_f32 v[142:143], v[142:143], v[156:157], v[78:79] op_sel_hi:[1,0,1]
	v_pk_fma_f32 v[160:161], v[140:141], v[156:157], v[76:77] op_sel_hi:[1,0,1]
	s_cbranch_vccz .LBB0_199
	s_and_b64 s[28:29], s[82:83], exec
	s_cselect_b32 s28, s77, 0x1000
	s_cselect_b32 s3, s69, s2
	v_add_u32_e32 v140, s28, v164
	s_lshl_b32 s3, s3, 1
	v_ashrrev_i32_e32 v141, 31, v140
	v_mad_i64_i32 v[140:141], s[28:29], s3, v247, v[140:141]
	v_lshlrev_b64 v[140:141], 8, v[140:141]
	v_lshl_add_u64 v[140:141], s[24:25], 0, v[140:141]
	v_lshl_add_u64 v[140:141], v[140:141], 0, v[208:209]
	v_cvt_pk_bf16_f32 v166, v160, v161
	v_cvt_pk_bf16_f32 v167, v142, v143
	global_store_dwordx2 v[140:141], v[166:167], off
	s_mov_b64 s[84:85], 0

; __device__ __forceinline__ unsigned pk2(float lo, float hi) { unsigned r; asm volatile("v_cvt_pk_bf16_f32 %0, %1, %2" : "=v"(r) : "v"(lo), "v"(hi)); return r; }
; __device__ __forceinline__ float rstd_of(float ss) { return __builtin_amdgcn_rsqf(ss * (1.0f / 1024.0f) + EPS); }
;     __device__ __forceinline__ void operator()(const f32x4 (&acc)[2][2][4][2], const Unit& u, int wr, int wc, int fr_, int fq_) const {
;     ...
;                 const int lr = lr0 + ai * 128 + m * 16, r = u.pm * 256 + lr; const float rs = rstd_of(rowss[r]);
; #pragma unroll
;                 for (int bj = 0; bj < 2; ++bj)
; #pragma unroll
;                     for (int n = 0; n < 2; ++n) {
;                         const f32x4 v = acc[ai][bj][m][n] * rs + bv[bj][n];
;                         if (u.pn < 5) { u32x2 w; w.x = pk2(v[0], v[1]); w.y = pk2(v[2], v[3]); *(u32x2*)(qk + (size_t)r * 1280 + col0 + bj * 128 + n * 16) = w; }
;                         else { const int d = wc * 32 + 16 * n + 4 * fq; int b, key;
;                             if (u.pm < 128) { b = u.pm >> 4; key = (u.pm & 15) * 256 + lr; } else { b = u.pm - 128; key = SEQ + lr; }
;                             u32x2 w; w.x = pk2(v[0], v[1]); w.y = pk2(v[2], v[3]);
;                             *(u32x2*)(vb + ((size_t)(b * 2 + bj) * KEYS + key) * 128 + d) = w; }
.LBB0_213:
	s_nop 1
	v_mov_b32_e32 v128, v172
	v_or_b32_e32 v134, 16, v164
	s_and_b64 vcc, exec, s[40:41]
	s_mov_b64 s[46:47], -1
	v_fmamk_f32 v128, v128, 0x3a800000, v213
	v_rsq_f32_e32 v128, v128
	s_nop 0
	v_pk_fma_f32 v[126:127], v[126:127], v[128:129], v[78:79] op_sel_hi:[1,0,1]
	v_pk_fma_f32 v[130:131], v[124:125], v[128:129], v[76:77] op_sel_hi:[1,0,1]
	s_cbranch_vccnz .LBB0_215
	s_and_b64 s[28:29], s[82:83], exec
	s_cselect_b32 s28, s77, 0x1000
	s_cselect_b32 s3, s69, s2
	v_add_u32_e32 v124, s28, v134
	s_lshl_b32 s3, s3, 1
	v_ashrrev_i32_e32 v125, 31, v124
	v_mad_i64_i32 v[124:125], s[28:29], s3, v247, v[124:125]
	v_lshlrev_b64 v[124:125], 8, v[124:125]
	v_lshl_add_u64 v[124:125], s[24:25], 0, v[124:125]
	v_lshl_add_u64 v[124:125], v[124:125], 0, v[208:209]
	s_mov_b64 s[46:47], 0
	v_cvt_pk_bf16_f32 v132, v130, v131
	v_cvt_pk_bf16_f32 v133, v126, v127
	global_store_dwordx2 v[124:125], v[132:133], off

; __device__ __forceinline__ unsigned pk2(float lo, float hi) { unsigned r; asm volatile("v_cvt_pk_bf16_f32 %0, %1, %2" : "=v"(r) : "v"(lo), "v"(hi)); return r; }
; __device__ __forceinline__ float rstd_of(float ss) { return __builtin_amdgcn_rsqf(ss * (1.0f / 1024.0f) + EPS); }
;     __device__ __forceinline__ void operator()(const f32x4 (&acc)[2][2][4][2], const Unit& u, int wr, int wc, int fr_, int fq_) const {
;     ...
;                 const int lr = lr0 + ai * 128 + m * 16, r = u.pm * 256 + lr; const float rs = rstd_of(rowss[r]);
; #pragma unroll
;                 for (int bj = 0; bj < 2; ++bj)
; #pragma unroll
;                     for (int n = 0; n < 2; ++n) {
;                         const f32x4 v = acc[ai][bj][m][n] * rs + bv[bj][n];
;                         if (u.pn < 5) { u32x2 w; w.x = pk2(v[0], v[1]); w.y = pk2(v[2], v[3]); *(u32x2*)(qk + (size_t)r * 1280 + col0 + bj * 128 + n * 16) = w; }
;                         else { const int d = wc * 32 + 16 * n + 4 * fq; int b, key;
;                             if (u.pm < 128) { b = u.pm >> 4; key = (u.pm & 15) * 256 + lr; } else { b = u.pm - 128; key = SEQ + lr; }
;                             u32x2 w; w.x = pk2(v[0], v[1]); w.y = pk2(v[2], v[3]);
;                             *(u32x2*)(vb + ((size_t)(b * 2 + bj) * KEYS + key) * 128 + d) = w; }
.LBB0_229:
	s_nop 1
	v_mov_b32_e32 v112, v173
	v_or_b32_e32 v118, 32, v164
	s_and_b64 vcc, exec, s[40:41]
	s_mov_b64 s[46:47], -1
	v_fmamk_f32 v112, v112, 0x3a800000, v213
	v_rsq_f32_e32 v112, v112
	s_nop 0
	v_pk_fma_f32 v[110:111], v[110:111], v[112:113], v[78:79] op_sel_hi:[1,0,1]
	v_pk_fma_f32 v[114:115], v[108:109], v[112:113], v[76:77] op_sel_hi:[1,0,1]
	s_cbranch_vccnz .LBB0_231
	s_and_b64 s[28:29], s[82:83], exec
	s_cselect_b32 s28, s77, 0x1000
	s_cselect_b32 s3, s69, s2
	v_add_u32_e32 v108, s28, v118
	s_lshl_b32 s3, s3, 1
	v_ashrrev_i32_e32 v109, 31, v108
	v_mad_i64_i32 v[108:109], s[28:29], s3, v247, v[108:109]
	v_lshlrev_b64 v[108:109], 8, v[108:109]
	v_lshl_add_u64 v[108:109], s[24:25], 0, v[108:109]
	v_lshl_add_u64 v[108:109], v[108:109], 0, v[208:209]
	s_mov_b64 s[46:47], 0
	v_cvt_pk_bf16_f32 v116, v114, v115
	v_cvt_pk_bf16_f32 v117, v110, v111
	global_store_dwordx2 v[108:109], v[116:117], off

; __device__ __forceinline__ unsigned pk2(float lo, float hi) { unsigned r; asm volatile("v_cvt_pk_bf16_f32 %0, %1, %2" : "=v"(r) : "v"(lo), "v"(hi)); return r; }
; __device__ __forceinline__ float rstd_of(float ss) { return __builtin_amdgcn_rsqf(ss * (1.0f / 1024.0f) + EPS); }
;     __device__ __forceinline__ void operator()(const f32x4 (&acc)[2][2][4][2], const Unit& u, int wr, int wc, int fr_, int fq_) const {
;     ...
;                 const int lr = lr0 + ai * 128 + m * 16, r = u.pm * 256 + lr; const float rs = rstd_of(rowss[r]);
; #pragma unroll
;                 for (int bj = 0; bj < 2; ++bj)
; #pragma unroll
;                     for (int n = 0; n < 2; ++n) {
;                         const f32x4 v = acc[ai][bj][m][n] * rs + bv[bj][n];
;                         if (u.pn < 5) { u32x2 w; w.x = pk2(v[0], v[1]); w.y = pk2(v[2], v[3]); *(u32x2*)(qk + (size_t)r * 1280 + col0 + bj * 128 + n * 16) = w; }
;                         else { const int d = wc * 32 + 16 * n + 4 * fq; int b, key;
;                             if (u.pm < 128) { b = u.pm >> 4; key = (u.pm & 15) * 256 + lr; } else { b = u.pm - 128; key = SEQ + lr; }
;                             u32x2 w; w.x = pk2(v[0], v[1]); w.y = pk2(v[2], v[3]);
;                             *(u32x2*)(vb + ((size_t)(b * 2 + bj) * KEYS + key) * 128 + d) = w; }
.LBB0_245:
	s_nop 1
	v_mov_b32_e32 v96, v174
	v_or_b32_e32 v102, 48, v164
	s_and_b64 vcc, exec, s[40:41]
	s_mov_b64 s[46:47], -1
	v_fmamk_f32 v96, v96, 0x3a800000, v213
	v_rsq_f32_e32 v96, v96
	s_nop 0
	v_pk_fma_f32 v[94:95], v[94:95], v[96:97], v[78:79] op_sel_hi:[1,0,1]
	v_pk_fma_f32 v[98:99], v[92:93], v[96:97], v[76:77] op_sel_hi:[1,0,1]
	s_cbranch_vccnz .LBB0_247
	s_and_b64 s[28:29], s[82:83], exec
	s_cselect_b32 s28, s77, 0x1000
	s_cselect_b32 s3, s69, s2
	v_add_u32_e32 v92, s28, v102
	s_lshl_b32 s3, s3, 1
	v_ashrrev_i32_e32 v93, 31, v92
	v_mad_i64_i32 v[92:93], s[28:29], s3, v247, v[92:93]
	v_lshlrev_b64 v[92:93], 8, v[92:93]
	v_lshl_add_u64 v[92:93], s[24:25], 0, v[92:93]
	v_lshl_add_u64 v[92:93], v[92:93], 0, v[208:209]
	s_mov_b64 s[46:47], 0
	v_cvt_pk_bf16_f32 v100, v98, v99
	v_cvt_pk_bf16_f32 v101, v94, v95
	global_store_dwordx2 v[92:93], v[100:101], off

; __device__ __forceinline__ unsigned pk2(float lo, float hi) { unsigned r; asm volatile("v_cvt_pk_bf16_f32 %0, %1, %2" : "=v"(r) : "v"(lo), "v"(hi)); return r; }
; __device__ __forceinline__ float rstd_of(float ss) { return __builtin_amdgcn_rsqf(ss * (1.0f / 1024.0f) + EPS); }
;     __device__ __forceinline__ void operator()(const f32x4 (&acc)[2][2][4][2], const Unit& u, int wr, int wc, int fr_, int fq_) const {
;     ...
;                 const int lr = lr0 + ai * 128 + m * 16, r = u.pm * 256 + lr; const float rs = rstd_of(rowss[r]);
; #pragma unroll
;                 for (int bj = 0; bj < 2; ++bj)
; #pragma unroll
;                     for (int n = 0; n < 2; ++n) {
;                         const f32x4 v = acc[ai][bj][m][n] * rs + bv[bj][n];
;                         if (u.pn < 5) { u32x2 w; w.x = pk2(v[0], v[1]); w.y = pk2(v[2], v[3]); *(u32x2*)(qk + (size_t)r * 1280 + col0 + bj * 128 + n * 16) = w; }
;                         else { const int d = wc * 32 + 16 * n + 4 * fq; int b, key;
;                             if (u.pm < 128) { b = u.pm >> 4; key = (u.pm & 15) * 256 + lr; } else { b = u.pm - 128; key = SEQ + lr; }
;                             u32x2 w; w.x = pk2(v[0], v[1]); w.y = pk2(v[2], v[3]);
;                             *(u32x2*)(vb + ((size_t)(b * 2 + bj) * KEYS + key) * 128 + d) = w; }
.LBB0_261:
	s_nop 1
	v_mov_b32_e32 v80, v175
	v_add_u32_e32 v86, 0x80, v164
	s_and_b64 vcc, exec, s[40:41]
	s_mov_b64 s[46:47], -1
	v_fmamk_f32 v80, v80, 0x3a800000, v213
	v_rsq_f32_e32 v80, v80
	s_nop 0
	v_pk_fma_f32 v[74:75], v[74:75], v[80:81], v[78:79] op_sel_hi:[1,0,1]
	v_pk_fma_f32 v[82:83], v[72:73], v[80:81], v[76:77] op_sel_hi:[1,0,1]
	s_cbranch_vccnz .LBB0_263
	s_and_b64 s[28:29], s[82:83], exec
	s_cselect_b32 s28, s77, 0x1000
	s_cselect_b32 s3, s69, s2
	v_add_u32_e32 v72, s28, v86
	s_lshl_b32 s3, s3, 1
	v_ashrrev_i32_e32 v73, 31, v72
	v_mad_i64_i32 v[72:73], s[28:29], s3, v247, v[72:73]
	v_lshlrev_b64 v[72:73], 8, v[72:73]
	v_lshl_add_u64 v[72:73], s[24:25], 0, v[72:73]
	v_lshl_add_u64 v[72:73], v[72:73], 0, v[208:209]
	s_mov_b64 s[46:47], 0
	v_cvt_pk_bf16_f32 v84, v82, v83
	v_cvt_pk_bf16_f32 v85, v74, v75
	global_store_dwordx2 v[72:73], v[84:85], off

; __device__ __forceinline__ unsigned pk2(float lo, float hi) { unsigned r; asm volatile("v_cvt_pk_bf16_f32 %0, %1, %2" : "=v"(r) : "v"(lo), "v"(hi)); return r; }
; __device__ __forceinline__ float rstd_of(float ss) { return __builtin_amdgcn_rsqf(ss * (1.0f / 1024.0f) + EPS); }
;     __device__ __forceinline__ void operator()(const f32x4 (&acc)[2][2][4][2], const Unit& u, int wr, int wc, int fr_, int fq_) const {
;     ...
;                 const int lr = lr0 + ai * 128 + m * 16, r = u.pm * 256 + lr; const float rs = rstd_of(rowss[r]);
; #pragma unroll
;                 for (int bj = 0; bj < 2; ++bj)
; #pragma unroll
;                     for (int n = 0; n < 2; ++n) {
;                         const f32x4 v = acc[ai][bj][m][n] * rs + bv[bj][n];
;                         if (u.pn < 5) { u32x2 w; w.x = pk2(v[0], v[1]); w.y = pk2(v[2], v[3]); *(u32x2*)(qk + (size_t)r * 1280 + col0 + bj * 128 + n * 16) = w; }
;                         else { const int d = wc * 32 + 16 * n + 4 * fq; int b, key;
;                             if (u.pm < 128) { b = u.pm >> 4; key = (u.pm & 15) * 256 + lr; } else { b = u.pm - 128; key = SEQ + lr; }
;                             u32x2 w; w.x = pk2(v[0], v[1]); w.y = pk2(v[2], v[3]);
;                             *(u32x2*)(vb + ((size_t)(b * 2 + bj) * KEYS + key) * 128 + d) = w; }
.LBB0_277:
	s_nop 1
	v_mov_b32_e32 v48, v176
	v_add_u32_e32 v58, 0x90, v164
	s_and_b64 vcc, exec, s[40:41]
	s_mov_b64 s[46:47], -1
	v_fmamk_f32 v48, v48, 0x3a800000, v213
	v_rsq_f32_e32 v48, v48
	s_nop 0
	v_pk_fma_f32 v[46:47], v[46:47], v[48:49], v[78:79] op_sel_hi:[1,0,1]
	v_pk_fma_f32 v[50:51], v[44:45], v[48:49], v[76:77] op_sel_hi:[1,0,1]
	s_cbranch_vccnz .LBB0_279
	s_and_b64 s[28:29], s[82:83], exec
	s_cselect_b32 s28, s77, 0x1000
	s_cselect_b32 s3, s69, s2
	v_add_u32_e32 v44, s28, v58
	s_lshl_b32 s3, s3, 1
	v_ashrrev_i32_e32 v45, 31, v44
	v_mad_i64_i32 v[44:45], s[28:29], s3, v247, v[44:45]
	v_lshlrev_b64 v[44:45], 8, v[44:45]
	v_lshl_add_u64 v[44:45], s[24:25], 0, v[44:45]
	v_lshl_add_u64 v[44:45], v[44:45], 0, v[208:209]
	s_mov_b64 s[46:47], 0
	v_cvt_pk_bf16_f32 v56, v50, v51
	v_cvt_pk_bf16_f32 v57, v46, v47
	global_store_dwordx2 v[44:45], v[56:57], off

; __device__ __forceinline__ unsigned pk2(float lo, float hi) { unsigned r; asm volatile("v_cvt_pk_bf16_f32 %0, %1, %2" : "=v"(r) : "v"(lo), "v"(hi)); return r; }
; __device__ __forceinline__ float rstd_of(float ss) { return __builtin_amdgcn_rsqf(ss * (1.0f / 1024.0f) + EPS); }
;     __device__ __forceinline__ void operator()(const f32x4 (&acc)[2][2][4][2], const Unit& u, int wr, int wc, int fr_, int fq_) const {
;     ...
;                 const int lr = lr0 + ai * 128 + m * 16, r = u.pm * 256 + lr; const float rs = rstd_of(rowss[r]);
; #pragma unroll
;                 for (int bj = 0; bj < 2; ++bj)
; #pragma unroll
;                     for (int n = 0; n < 2; ++n) {
;                         const f32x4 v = acc[ai][bj][m][n] * rs + bv[bj][n];
;                         if (u.pn < 5) { u32x2 w; w.x = pk2(v[0], v[1]); w.y = pk2(v[2], v[3]); *(u32x2*)(qk + (size_t)r * 1280 + col0 + bj * 128 + n * 16) = w; }
;                         else { const int d = wc * 32 + 16 * n + 4 * fq; int b, key;
;                             if (u.pm < 128) { b = u.pm >> 4; key = (u.pm & 15) * 256 + lr; } else { b = u.pm - 128; key = SEQ + lr; }
;                             u32x2 w; w.x = pk2(v[0], v[1]); w.y = pk2(v[2], v[3]);
;                             *(u32x2*)(vb + ((size_t)(b * 2 + bj) * KEYS + key) * 128 + d) = w; }
.LBB0_293:
	s_nop 1
	v_mov_b32_e32 v32, v177
	v_add_u32_e32 v38, 0xa0, v164
	s_and_b64 vcc, exec, s[40:41]
	s_mov_b64 s[46:47], -1
	v_fmamk_f32 v32, v32, 0x3a800000, v213
	v_rsq_f32_e32 v32, v32
	s_nop 0
	v_pk_fma_f32 v[30:31], v[30:31], v[32:33], v[78:79] op_sel_hi:[1,0,1]
	v_pk_fma_f32 v[34:35], v[28:29], v[32:33], v[76:77] op_sel_hi:[1,0,1]
	s_cbranch_vccnz .LBB0_295
	s_and_b64 s[28:29], s[82:83], exec
	s_cselect_b32 s28, s77, 0x1000
	s_cselect_b32 s3, s69, s2
	v_add_u32_e32 v28, s28, v38
	s_lshl_b32 s3, s3, 1
	v_ashrrev_i32_e32 v29, 31, v28
	v_mad_i64_i32 v[28:29], s[28:29], s3, v247, v[28:29]
	v_lshlrev_b64 v[28:29], 8, v[28:29]
	v_lshl_add_u64 v[28:29], s[24:25], 0, v[28:29]
	v_lshl_add_u64 v[28:29], v[28:29], 0, v[208:209]
	s_mov_b64 s[46:47], 0
	v_cvt_pk_bf16_f32 v36, v34, v35
	v_cvt_pk_bf16_f32 v37, v30, v31
	global_store_dwordx2 v[28:29], v[36:37], off

; __device__ __forceinline__ unsigned pk2(float lo, float hi) { unsigned r; asm volatile("v_cvt_pk_bf16_f32 %0, %1, %2" : "=v"(r) : "v"(lo), "v"(hi)); return r; }
; __device__ __forceinline__ float rstd_of(float ss) { return __builtin_amdgcn_rsqf(ss * (1.0f / 1024.0f) + EPS); }
;     __device__ __forceinline__ void operator()(const f32x4 (&acc)[2][2][4][2], const Unit& u, int wr, int wc, int fr_, int fq_) const {
;     ...
;                 const int lr = lr0 + ai * 128 + m * 16, r = u.pm * 256 + lr; const float rs = rstd_of(rowss[r]);
; #pragma unroll
;                 for (int bj = 0; bj < 2; ++bj)
; #pragma unroll
;                     for (int n = 0; n < 2; ++n) {
;                         const f32x4 v = acc[ai][bj][m][n] * rs + bv[bj][n];
;                         if (u.pn < 5) { u32x2 w; w.x = pk2(v[0], v[1]); w.y = pk2(v[2], v[3]); *(u32x2*)(qk + (size_t)r * 1280 + col0 + bj * 128 + n * 16) = w; }
;                         else { const int d = wc * 32 + 16 * n + 4 * fq; int b, key;
;                             if (u.pm < 128) { b = u.pm >> 4; key = (u.pm & 15) * 256 + lr; } else { b = u.pm - 128; key = SEQ + lr; }
;                             u32x2 w; w.x = pk2(v[0], v[1]); w.y = pk2(v[2], v[3]);
;                             *(u32x2*)(vb + ((size_t)(b * 2 + bj) * KEYS + key) * 128 + d) = w; }
.LBB0_309:
	s_nop 1
	v_mov_b32_e32 v16, v178
	v_add_u32_e32 v22, 0xb0, v164
	s_and_b64 vcc, exec, s[40:41]
	s_mov_b64 s[46:47], -1
	v_fmamk_f32 v16, v16, 0x3a800000, v213
	v_rsq_f32_e32 v16, v16
	s_nop 0
	v_pk_fma_f32 v[14:15], v[14:15], v[16:17], v[78:79] op_sel_hi:[1,0,1]
	v_pk_fma_f32 v[18:19], v[12:13], v[16:17], v[76:77] op_sel_hi:[1,0,1]
	s_cbranch_vccnz .LBB0_311
	s_and_b64 s[28:29], s[82:83], exec
	s_cselect_b32 s28, s77, 0x1000
	s_cselect_b32 s3, s69, s2
	v_add_u32_e32 v12, s28, v22
	s_lshl_b32 s3, s3, 1
	v_ashrrev_i32_e32 v13, 31, v12
	v_mad_i64_i32 v[12:13], s[28:29], s3, v247, v[12:13]
	v_lshlrev_b64 v[12:13], 8, v[12:13]
	v_lshl_add_u64 v[12:13], s[24:25], 0, v[12:13]
	v_lshl_add_u64 v[12:13], v[12:13], 0, v[208:209]
	s_mov_b64 s[46:47], 0
	v_cvt_pk_bf16_f32 v20, v18, v19
	v_cvt_pk_bf16_f32 v21, v14, v15
	global_store_dwordx2 v[12:13], v[20:21], off

; __device__ __forceinline__ unsigned pk2(float lo, float hi) { unsigned r; asm volatile("v_cvt_pk_bf16_f32 %0, %1, %2" : "=v"(r) : "v"(lo), "v"(hi)); return r; }
; __device__ __forceinline__ float rstd_of(float ss) { return __builtin_amdgcn_rsqf(ss * (1.0f / 1024.0f) + EPS); }
;     __device__ __forceinline__ void operator()(const f32x4 (&acc)[2][2][4][2], const Unit& u, int wr, int wc, int fr_, int fq_) const {
;     ...
;         const int mb = mb_of_panel(u.pm), row0 = u.pm * 256 + wr * 64 + fr, col0 = u.pn * 256 + wc * 32 + 8 * fq;
;         f32x4 bv[2][2];
; #pragma unroll
;         for (int bj = 0; bj < 2; ++bj)
; #pragma unroll
;             for (int n = 0; n < 2; ++n) bv[bj][n] = *(const f32x4*)(sw + (size_t)mb * NGU + col0 + bj * 128 + 4 * n);
; #pragma unroll
;         for (int ai = 0; ai < 2; ++ai)
; #pragma unroll
;             for (int m = 0; m < 4; ++m) {
;                 const int r = row0 + ai * 128 + m * 16; const float rs = rstd_of(rowss[r]);
; #pragma unroll
;                 for (int bj = 0; bj < 2; ++bj) {
;                     const f32x4 v0 = acc[ai][bj][m][0] * rs + bv[bj][0], v1 = acc[ai][bj][m][1] * rs + bv[bj][1];
;                     u32x4 w; w.x = pk2(gelu_tanh_f(v0[0]), gelu_tanh_f(v0[1])); w.y = pk2(gelu_tanh_f(v0[2]), gelu_tanh_f(v0[3]));
;                     w.z = pk2(gelu_tanh_f(v1[0]), gelu_tanh_f(v1[1])); w.w = pk2(gelu_tanh_f(v1[2]), gelu_tanh_f(v1[3]));
;                     *(u32x4*)(O + (size_t)r * 1024 + col0 + bj * 128) = w;
.LBB0_466:
	v_mov_b32_e32 v154, v211
	s_min_i32 s3, s76, 0x80
	s_ashr_i32 s3, s3, 4
	s_lshl_b32 s27, s76, 8
	s_lshl_b32 s2, s2, 8
	v_lshrrev_b32_e32 v32, 1, v154
	s_add_i32 s27, s27, s87
	v_and_or_b32 v32, v32, 24, s2
	s_mul_hi_i32 s2, s3, 0x5800
	s_mulk_i32 s3, 0x5800
	v_or_b32_e32 v158, s58, v32
	s_add_u32 s28, s51, s3
	v_and_or_b32 v156, v154, 15, s27
	s_addc_u32 s29, s54, s2
	v_ashrrev_i32_e32 v159, 31, v158
	v_ashrrev_i32_e32 v157, 31, v156
	v_lshl_add_u64 v[36:37], v[158:159], 2, s[28:29]
	v_lshl_add_u64 v[154:155], v[156:157], 2, s[62:63]
	global_load_dwordx4 v[48:51], v[36:37], off offset:16
	global_load_dwordx4 v[52:55], v[36:37], off
	global_load_dwordx4 v[32:35], v[36:37], off offset:528
	s_nop 0
	global_load_dwordx4 v[36:39], v[36:37], off offset:512
	v_readlane_b32 s2, v254, 39
	global_load_dword v160, v[154:155], off
	global_load_dword v178, v[154:155], off offset:64
	global_load_dword v179, v[154:155], off offset:128
	global_load_dword v180, v[154:155], off offset:192
	global_load_dword v181, v[154:155], off offset:512
	global_load_dword v182, v[154:155], off offset:576
	global_load_dword v183, v[154:155], off offset:640
	global_load_dword v184, v[154:155], off offset:704
	v_lshlrev_b64 v[162:163], 11, v[156:157]
	v_readlane_b32 s3, v254, 40
	s_mov_b64 s[28:29], 0x40000
	s_mov_b64 s[46:47], -1
	s_brev_b32 s44, 60
	s_waitcnt vmcnt(0)
	v_fmamk_f32 v160, v160, 0x3a800000, v213
	v_rsq_f32_e32 v160, v160
	s_nop 0
	v_pk_fma_f32 v[140:141], v[140:141], v[160:161], v[52:53] op_sel_hi:[1,0,1]
	v_pk_fma_f32 v[166:167], v[138:139], v[160:161], v[50:51] op_sel_hi:[1,0,1]
	v_pk_fma_f32 v[138:139], v[136:137], v[160:161], v[48:49] op_sel_hi:[1,0,1]
	v_mul_f32_e32 v136, 0x3d922279, v140
	v_mul_f32_e32 v137, 0x3d922279, v141
	v_fmaak_f32 v136, v140, v136, 0x3fcc422a
	v_fmaak_f32 v137, v141, v137, 0x3fcc422a
	v_mul_f32_e32 v136, v140, v136
	v_mul_f32_e32 v137, v141, v137
	v_mul_f32_e32 v136, 0xbfb8aa3b, v136
	v_mul_f32_e32 v137, 0xbfb8aa3b, v137
	v_exp_f32_e32 v136, v136
	v_exp_f32_e32 v137, v137
	v_pk_fma_f32 v[142:143], v[142:143], v[160:161], v[54:55] op_sel_hi:[1,0,1]
	v_pk_fma_f32 v[132:133], v[132:133], v[160:161], v[36:37] op_sel_hi:[1,0,1]
	v_add_f32_e32 v136, 1.0, v136
	v_add_f32_e32 v137, 1.0, v137
	v_rcp_f32_e32 v136, v136
	v_rcp_f32_e32 v137, v137
	v_pk_fma_f32 v[134:135], v[134:135], v[160:161], v[38:39] op_sel_hi:[1,0,1]
	v_pk_fma_f32 v[128:129], v[128:129], v[160:161], v[32:33] op_sel_hi:[1,0,1]
	v_mul_f32_e32 v136, v140, v136
	v_mul_f32_e32 v137, v141, v137
	v_cvt_pk_bf16_f32 v136, v136, v137
	v_mul_f32_e32 v137, 0x3d922279, v142
	v_mul_f32_e32 v140, 0x3d922279, v143
	v_fmaak_f32 v137, v142, v137, 0x3fcc422a
	v_fmaak_f32 v140, v143, v140, 0x3fcc422a
	v_mul_f32_e32 v137, v142, v137
	v_mul_f32_e32 v140, v143, v140
	v_mul_f32_e32 v137, 0xbfb8aa3b, v137
	v_mul_f32_e32 v140, 0xbfb8aa3b, v140
	v_exp_f32_e32 v137, v137
	v_exp_f32_e32 v140, v140
	v_pk_fma_f32 v[130:131], v[130:131], v[160:161], v[34:35] op_sel_hi:[1,0,1]
	v_add_f32_e32 v137, 1.0, v137
	v_add_f32_e32 v140, 1.0, v140
	v_rcp_f32_e32 v137, v137
	v_rcp_f32_e32 v140, v140
	v_mul_f32_e32 v137, v142, v137
	v_mul_f32_e32 v140, v143, v140
	v_cvt_pk_bf16_f32 v137, v137, v140
	v_mul_f32_e32 v140, 0x3d922279, v138
	v_fmaak_f32 v140, v138, v140, 0x3fcc422a
	v_mul_f32_e32 v140, v138, v140
	v_mul_f32_e32 v140, 0xbfb8aa3b, v140
	v_exp_f32_e32 v140, v140
	v_lshlrev_b64 v[142:143], 1, v[158:159]
	v_add_f32_e32 v140, 1.0, v140
	v_rcp_f32_e32 v140, v140
	s_nop 0
	v_mul_f32_e32 v138, v138, v140
	v_mul_f32_e32 v140, 0x3d922279, v139
	v_fmaak_f32 v140, v139, v140, 0x3fcc422a
	v_mul_f32_e32 v140, v139, v140
	v_mul_f32_e32 v140, 0xbfb8aa3b, v140
	v_exp_f32_e32 v140, v140
	s_nop 0
	v_add_f32_e32 v140, 1.0, v140
	v_rcp_f32_e32 v140, v140
	s_nop 0
	v_mul_f32_e32 v139, v139, v140
	v_cvt_pk_bf16_f32 v138, v138, v139
	v_mul_f32_e32 v139, 0x3d922279, v166
	v_mul_f32_e32 v140, 0x3d922279, v167
	v_fmaak_f32 v139, v166, v139, 0x3fcc422a
	v_fmaak_f32 v140, v167, v140, 0x3fcc422a
	v_mul_f32_e32 v139, v166, v139
	v_mul_f32_e32 v140, v167, v140
	v_mul_f32_e32 v139, 0xbfb8aa3b, v139
	v_mul_f32_e32 v140, 0xbfb8aa3b, v140
	v_exp_f32_e32 v139, v139
	v_exp_f32_e32 v140, v140
	v_add_f32_e32 v139, 1.0, v139
	v_add_f32_e32 v140, 1.0, v140
	v_rcp_f32_e32 v139, v139
	v_rcp_f32_e32 v140, v140
	v_mul_f32_e32 v139, v166, v139
	v_mul_f32_e32 v140, v167, v140
	v_cvt_pk_bf16_f32 v139, v139, v140
	v_lshl_add_u64 v[140:141], s[2:3], 0, v[162:163]
	v_lshl_add_u64 v[140:141], v[140:141], 0, v[142:143]
	global_store_dwordx4 v[140:141], v[136:139], off
	s_nop 1
	v_mul_f32_e32 v136, 0x3d922279, v132
	v_fmaak_f32 v136, v132, v136, 0x3fcc422a
	v_mul_f32_e32 v136, v132, v136
	v_mul_f32_e32 v136, 0xbfb8aa3b, v136
	v_exp_f32_e32 v136, v136
	s_nop 0
	v_add_f32_e32 v136, 1.0, v136
	v_rcp_f32_e32 v136, v136
	s_nop 0
	v_mul_f32_e32 v132, v132, v136
	v_mul_f32_e32 v136, 0x3d922279, v133
	v_fmaak_f32 v136, v133, v136, 0x3fcc422a
	v_mul_f32_e32 v136, v133, v136
	v_mul_f32_e32 v136, 0xbfb8aa3b, v136
	v_exp_f32_e32 v136, v136
	s_nop 0
	v_add_f32_e32 v136, 1.0, v136
	v_rcp_f32_e32 v136, v136
	s_nop 0
	v_mul_f32_e32 v133, v133, v136
	v_cvt_pk_bf16_f32 v132, v132, v133
	v_mul_f32_e32 v133, 0x3d922279, v134
	v_fmaak_f32 v133, v134, v133, 0x3fcc422a
	v_mul_f32_e32 v133, v134, v133
	v_mul_f32_e32 v133, 0xbfb8aa3b, v133
	v_exp_f32_e32 v133, v133
	s_nop 0
	v_add_f32_e32 v133, 1.0, v133
	v_rcp_f32_e32 v133, v133
	s_nop 0
	v_mul_f32_e32 v133, v134, v133
	v_mul_f32_e32 v134, 0x3d922279, v135
	v_fmaak_f32 v134, v135, v134, 0x3fcc422a
	v_mul_f32_e32 v134, v135, v134
	v_mul_f32_e32 v134, 0xbfb8aa3b, v134
	v_exp_f32_e32 v134, v134
	s_nop 0
; __device__ __forceinline__ unsigned pk2(float lo, float hi) { unsigned r; asm volatile("v_cvt_pk_bf16_f32 %0, %1, %2" : "=v"(r) : "v"(lo), "v"(hi)); return r; }
; __device__ __forceinline__ float rstd_of(float ss) { return __builtin_amdgcn_rsqf(ss * (1.0f / 1024.0f) + EPS); }
; __device__ __forceinline__ float gelu_tanh_f(float v) {
;     const float z2 = v * (1.5957691216057308f + 0.07135481627159493f * v * v);
;     return v * __builtin_amdgcn_rcpf(1.0f + __builtin_amdgcn_exp2f(-1.4426950408889634f * z2));
; }
;     __device__ __forceinline__ void operator()(const f32x4 (&acc)[2][2][4][2], const Unit& u, int wr, int wc, int fr_, int fq_) const {
;     ...
;         for (int ai = 0; ai < 2; ++ai)
; #pragma unroll
;             for (int m = 0; m < 4; ++m) {
;                 const int r = row0 + ai * 128 + m * 16; const float rs = rstd_of(rowss[r]);
; #pragma unroll
;                 for (int bj = 0; bj < 2; ++bj) {
;                     const f32x4 v0 = acc[ai][bj][m][0] * rs + bv[bj][0], v1 = acc[ai][bj][m][1] * rs + bv[bj][1];
;                     u32x4 w; w.x = pk2(gelu_tanh_f(v0[0]), gelu_tanh_f(v0[1])); w.y = pk2(gelu_tanh_f(v0[2]), gelu_tanh_f(v0[3]));
;                     w.z = pk2(gelu_tanh_f(v1[0]), gelu_tanh_f(v1[1])); w.w = pk2(gelu_tanh_f(v1[2]), gelu_tanh_f(v1[3]));
;                     *(u32x4*)(O + (size_t)r * 1024 + col0 + bj * 128) = w;
	v_add_f32_e32 v134, 1.0, v134
	v_rcp_f32_e32 v134, v134
	s_nop 0
	v_mul_f32_e32 v134, v135, v134
	v_cvt_pk_bf16_f32 v133, v133, v134
	v_mul_f32_e32 v134, 0x3d922279, v128
	v_fmaak_f32 v134, v128, v134, 0x3fcc422a
	v_mul_f32_e32 v134, v128, v134
	v_mul_f32_e32 v134, 0xbfb8aa3b, v134
	v_exp_f32_e32 v134, v134
	s_nop 0
	v_add_f32_e32 v134, 1.0, v134
	v_rcp_f32_e32 v134, v134
	s_nop 0
	v_mul_f32_e32 v128, v128, v134
	v_mul_f32_e32 v134, 0x3d922279, v129
	v_fmaak_f32 v134, v129, v134, 0x3fcc422a
	v_mul_f32_e32 v134, v129, v134
	v_mul_f32_e32 v134, 0xbfb8aa3b, v134
	v_exp_f32_e32 v134, v134
	s_nop 0
	v_add_f32_e32 v134, 1.0, v134
	v_rcp_f32_e32 v134, v134
	s_nop 0
	v_mul_f32_e32 v129, v129, v134
	v_cvt_pk_bf16_f32 v134, v128, v129
	v_mul_f32_e32 v128, 0x3d922279, v130
	v_mul_f32_e32 v129, 0x3d922279, v131
	v_fmaak_f32 v128, v130, v128, 0x3fcc422a
	v_fmaak_f32 v129, v131, v129, 0x3fcc422a
	v_mul_f32_e32 v128, v130, v128
	v_mul_f32_e32 v129, v131, v129
	v_mul_f32_e32 v128, 0xbfb8aa3b, v128
	v_mul_f32_e32 v129, 0xbfb8aa3b, v129
	v_exp_f32_e32 v128, v128
	v_exp_f32_e32 v129, v129
	v_add_f32_e32 v128, 1.0, v128
	v_add_f32_e32 v129, 1.0, v129
	v_rcp_f32_e32 v128, v128
	v_rcp_f32_e32 v129, v129
	v_mul_f32_e32 v128, v130, v128
	v_mul_f32_e32 v129, v131, v129
	v_cvt_pk_bf16_f32 v135, v128, v129
	global_store_dwordx4 v[140:141], v[132:135], off offset:256
	s_nop 1
	v_mov_b32_e32 v128, v178
	v_or_b32_e32 v130, 16, v156
	v_ashrrev_i32_e32 v131, 31, v130
	v_lshlrev_b64 v[130:131], 11, v[130:131]
	v_fmamk_f32 v128, v128, 0x3a800000, v213
	v_rsq_f32_e32 v128, v128
	s_nop 0
	v_pk_fma_f32 v[124:125], v[124:125], v[128:129], v[52:53] op_sel_hi:[1,0,1]
	v_pk_fma_f32 v[126:127], v[126:127], v[128:129], v[54:55] op_sel_hi:[1,0,1]
	v_pk_fma_f32 v[122:123], v[122:123], v[128:129], v[50:51] op_sel_hi:[1,0,1]
	v_pk_fma_f32 v[120:121], v[120:121], v[128:129], v[48:49] op_sel_hi:[1,0,1]
	v_mul_f32_e32 v129, 0x3d922279, v124
	v_fmaak_f32 v129, v124, v129, 0x3fcc422a
	v_mul_f32_e32 v129, v124, v129
	v_mul_f32_e32 v129, 0xbfb8aa3b, v129
	v_exp_f32_e32 v129, v129
	s_nop 0
	v_add_f32_e32 v129, 1.0, v129
	v_rcp_f32_e32 v129, v129
	s_nop 0
	v_mul_f32_e32 v124, v124, v129
	v_mul_f32_e32 v129, 0x3d922279, v125
	v_fmaak_f32 v129, v125, v129, 0x3fcc422a
	v_mul_f32_e32 v129, v125, v129
	v_mul_f32_e32 v129, 0xbfb8aa3b, v129
	v_exp_f32_e32 v129, v129
	s_nop 0
	v_add_f32_e32 v129, 1.0, v129
	v_rcp_f32_e32 v129, v129
	s_nop 0
	v_mul_f32_e32 v125, v125, v129
	v_cvt_pk_bf16_f32 v124, v124, v125
	v_mul_f32_e32 v125, 0x3d922279, v126
	v_fmaak_f32 v125, v126, v125, 0x3fcc422a
	v_mul_f32_e32 v125, v126, v125
	v_mul_f32_e32 v125, 0xbfb8aa3b, v125
	v_exp_f32_e32 v125, v125
	v_pk_fma_f32 v[116:117], v[116:117], v[128:129], v[36:37] op_sel_hi:[1,0,1]
	v_pk_fma_f32 v[118:119], v[118:119], v[128:129], v[38:39] op_sel_hi:[1,0,1]
	v_add_f32_e32 v125, 1.0, v125
	v_rcp_f32_e32 v125, v125
	s_nop 0
	v_mul_f32_e32 v125, v126, v125
	v_mul_f32_e32 v126, 0x3d922279, v127
	v_fmaak_f32 v126, v127, v126, 0x3fcc422a
	v_mul_f32_e32 v126, v127, v126
	v_mul_f32_e32 v126, 0xbfb8aa3b, v126
	v_exp_f32_e32 v126, v126
	s_nop 0
	v_add_f32_e32 v126, 1.0, v126
	v_rcp_f32_e32 v126, v126
	s_nop 0
	v_mul_f32_e32 v126, v127, v126
	v_cvt_pk_bf16_f32 v125, v125, v126
	v_mul_f32_e32 v126, 0x3d922279, v120
	v_fmaak_f32 v126, v120, v126, 0x3fcc422a
	v_mul_f32_e32 v126, v120, v126
	v_mul_f32_e32 v126, 0xbfb8aa3b, v126
	v_exp_f32_e32 v126, v126
	s_nop 0
	v_add_f32_e32 v126, 1.0, v126
	v_rcp_f32_e32 v126, v126
	s_nop 0
	v_mul_f32_e32 v120, v120, v126
	v_mul_f32_e32 v126, 0x3d922279, v121
	v_fmaak_f32 v126, v121, v126, 0x3fcc422a
	v_mul_f32_e32 v126, v121, v126
	v_mul_f32_e32 v126, 0xbfb8aa3b, v126
	v_exp_f32_e32 v126, v126
	s_nop 0
	v_add_f32_e32 v126, 1.0, v126
	v_rcp_f32_e32 v126, v126
	s_nop 0
	v_mul_f32_e32 v121, v121, v126
	v_cvt_pk_bf16_f32 v126, v120, v121
	v_mul_f32_e32 v120, 0x3d922279, v122
	v_mul_f32_e32 v121, 0x3d922279, v123
	v_fmaak_f32 v120, v122, v120, 0x3fcc422a
	v_fmaak_f32 v121, v123, v121, 0x3fcc422a
	v_mul_f32_e32 v120, v122, v120
	v_mul_f32_e32 v121, v123, v121
	v_mul_f32_e32 v120, 0xbfb8aa3b, v120
	v_mul_f32_e32 v121, 0xbfb8aa3b, v121
	v_exp_f32_e32 v120, v120
	v_exp_f32_e32 v121, v121
	v_add_f32_e32 v120, 1.0, v120
	v_add_f32_e32 v121, 1.0, v121
	v_rcp_f32_e32 v120, v120
	v_rcp_f32_e32 v121, v121
	v_mul_f32_e32 v120, v122, v120
	v_mul_f32_e32 v121, v123, v121
	v_pk_fma_f32 v[122:123], v[114:115], v[128:129], v[34:35] op_sel_hi:[1,0,1]
	v_pk_fma_f32 v[114:115], v[112:113], v[128:129], v[32:33] op_sel_hi:[1,0,1]
	v_mul_f32_e32 v112, 0x3d922279, v116
	v_mul_f32_e32 v113, 0x3d922279, v117
	v_fmaak_f32 v112, v116, v112, 0x3fcc422a
	v_fmaak_f32 v113, v117, v113, 0x3fcc422a
	v_mul_f32_e32 v112, v116, v112
	v_mul_f32_e32 v113, v117, v113
	v_mul_f32_e32 v112, 0xbfb8aa3b, v112
	v_mul_f32_e32 v113, 0xbfb8aa3b, v113
	v_exp_f32_e32 v112, v112
	v_exp_f32_e32 v113, v113
	v_cvt_pk_bf16_f32 v127, v120, v121
	v_lshl_add_u64 v[120:121], s[2:3], 0, v[130:131]
	v_add_f32_e32 v112, 1.0, v112
	v_add_f32_e32 v113, 1.0, v113
	v_rcp_f32_e32 v112, v112
	v_rcp_f32_e32 v113, v113
	v_lshl_add_u64 v[120:121], v[120:121], 0, v[142:143]
	global_store_dwordx4 v[120:121], v[124:127], off
	v_mul_f32_e32 v112, v116, v112
	v_mul_f32_e32 v113, v117, v113
	v_cvt_pk_bf16_f32 v112, v112, v113
	v_mul_f32_e32 v113, 0x3d922279, v118
	v_mul_f32_e32 v116, 0x3d922279, v119
	v_fmaak_f32 v113, v118, v113, 0x3fcc422a
	v_fmaak_f32 v116, v119, v116, 0x3fcc422a
	v_mul_f32_e32 v113, v118, v113
	v_mul_f32_e32 v116, v119, v116
	v_mul_f32_e32 v113, 0xbfb8aa3b, v113
	v_mul_f32_e32 v116, 0xbfb8aa3b, v116
	v_exp_f32_e32 v113, v113
	v_exp_f32_e32 v116, v116
; __device__ __forceinline__ unsigned pk2(float lo, float hi) { unsigned r; asm volatile("v_cvt_pk_bf16_f32 %0, %1, %2" : "=v"(r) : "v"(lo), "v"(hi)); return r; }
; __device__ __forceinline__ float rstd_of(float ss) { return __builtin_amdgcn_rsqf(ss * (1.0f / 1024.0f) + EPS); }
; __device__ __forceinline__ float gelu_tanh_f(float v) {
;     const float z2 = v * (1.5957691216057308f + 0.07135481627159493f * v * v);
;     return v * __builtin_amdgcn_rcpf(1.0f + __builtin_amdgcn_exp2f(-1.4426950408889634f * z2));
; }
;     __device__ __forceinline__ void operator()(const f32x4 (&acc)[2][2][4][2], const Unit& u, int wr, int wc, int fr_, int fq_) const {
;     ...
;         for (int ai = 0; ai < 2; ++ai)
; #pragma unroll
;             for (int m = 0; m < 4; ++m) {
;                 const int r = row0 + ai * 128 + m * 16; const float rs = rstd_of(rowss[r]);
; #pragma unroll
;                 for (int bj = 0; bj < 2; ++bj) {
;                     const f32x4 v0 = acc[ai][bj][m][0] * rs + bv[bj][0], v1 = acc[ai][bj][m][1] * rs + bv[bj][1];
;                     u32x4 w; w.x = pk2(gelu_tanh_f(v0[0]), gelu_tanh_f(v0[1])); w.y = pk2(gelu_tanh_f(v0[2]), gelu_tanh_f(v0[3]));
;                     w.z = pk2(gelu_tanh_f(v1[0]), gelu_tanh_f(v1[1])); w.w = pk2(gelu_tanh_f(v1[2]), gelu_tanh_f(v1[3]));
;                     *(u32x4*)(O + (size_t)r * 1024 + col0 + bj * 128) = w;
	v_add_f32_e32 v113, 1.0, v113
	v_add_f32_e32 v116, 1.0, v116
	v_rcp_f32_e32 v113, v113
	v_rcp_f32_e32 v116, v116
	v_mul_f32_e32 v113, v118, v113
	v_mul_f32_e32 v116, v119, v116
	v_cvt_pk_bf16_f32 v113, v113, v116
	v_mul_f32_e32 v116, 0x3d922279, v114
	v_fmaak_f32 v116, v114, v116, 0x3fcc422a
	v_mul_f32_e32 v116, v114, v116
	v_mul_f32_e32 v116, 0xbfb8aa3b, v116
	v_exp_f32_e32 v116, v116
	s_nop 0
	v_add_f32_e32 v116, 1.0, v116
	v_rcp_f32_e32 v116, v116
	s_nop 0
	v_mul_f32_e32 v114, v114, v116
	v_mul_f32_e32 v116, 0x3d922279, v115
	v_fmaak_f32 v116, v115, v116, 0x3fcc422a
	v_mul_f32_e32 v116, v115, v116
	v_mul_f32_e32 v116, 0xbfb8aa3b, v116
	v_exp_f32_e32 v116, v116
	s_nop 0
	v_add_f32_e32 v116, 1.0, v116
	v_rcp_f32_e32 v116, v116
	s_nop 0
	v_mul_f32_e32 v115, v115, v116
	v_cvt_pk_bf16_f32 v114, v114, v115
	v_mul_f32_e32 v115, 0x3d922279, v122
	v_fmaak_f32 v115, v122, v115, 0x3fcc422a
	v_mul_f32_e32 v116, 0x3d922279, v123
	v_mul_f32_e32 v115, v122, v115
	v_fmaak_f32 v116, v123, v116, 0x3fcc422a
	v_mul_f32_e32 v115, 0xbfb8aa3b, v115
	v_mul_f32_e32 v116, v123, v116
	v_exp_f32_e32 v115, v115
	v_mul_f32_e32 v116, 0xbfb8aa3b, v116
	v_exp_f32_e32 v116, v116
	v_add_f32_e32 v115, 1.0, v115
	v_rcp_f32_e32 v115, v115
	v_add_f32_e32 v116, 1.0, v116
	v_rcp_f32_e32 v116, v116
	v_mul_f32_e32 v115, v122, v115
	v_mul_f32_e32 v116, v123, v116
	v_cvt_pk_bf16_f32 v115, v115, v116
	global_store_dwordx4 v[120:121], v[112:115], off offset:256
	s_nop 1
	v_mov_b32_e32 v114, v179
	s_nop 0
	v_or_b32_e32 v112, 32, v156
	v_ashrrev_i32_e32 v113, 31, v112
	v_lshlrev_b64 v[112:113], 11, v[112:113]
	v_fmamk_f32 v114, v114, 0x3a800000, v213
	v_rsq_f32_e32 v114, v114
	s_nop 0
	v_pk_fma_f32 v[108:109], v[108:109], v[114:115], v[52:53] op_sel_hi:[1,0,1]
	v_pk_fma_f32 v[116:117], v[106:107], v[114:115], v[50:51] op_sel_hi:[1,0,1]
	v_pk_fma_f32 v[106:107], v[104:105], v[114:115], v[48:49] op_sel_hi:[1,0,1]
	v_mul_f32_e32 v104, 0x3d922279, v108
	v_mul_f32_e32 v105, 0x3d922279, v109
	v_fmaak_f32 v104, v108, v104, 0x3fcc422a
	v_fmaak_f32 v105, v109, v105, 0x3fcc422a
	v_mul_f32_e32 v104, v108, v104
	v_mul_f32_e32 v105, v109, v105
	v_mul_f32_e32 v104, 0xbfb8aa3b, v104
	v_mul_f32_e32 v105, 0xbfb8aa3b, v105
	v_exp_f32_e32 v104, v104
	v_exp_f32_e32 v105, v105
	v_pk_fma_f32 v[110:111], v[110:111], v[114:115], v[54:55] op_sel_hi:[1,0,1]
	v_pk_fma_f32 v[100:101], v[100:101], v[114:115], v[36:37] op_sel_hi:[1,0,1]
	v_add_f32_e32 v104, 1.0, v104
	v_add_f32_e32 v105, 1.0, v105
	v_rcp_f32_e32 v104, v104
	v_rcp_f32_e32 v105, v105
	v_pk_fma_f32 v[102:103], v[102:103], v[114:115], v[38:39] op_sel_hi:[1,0,1]
	v_mul_f32_e32 v104, v108, v104
	v_mul_f32_e32 v105, v109, v105
	v_cvt_pk_bf16_f32 v104, v104, v105
	v_mul_f32_e32 v105, 0x3d922279, v110
	v_mul_f32_e32 v108, 0x3d922279, v111
	v_fmaak_f32 v105, v110, v105, 0x3fcc422a
	v_fmaak_f32 v108, v111, v108, 0x3fcc422a
	v_mul_f32_e32 v105, v110, v105
	v_mul_f32_e32 v108, v111, v108
	v_mul_f32_e32 v105, 0xbfb8aa3b, v105
	v_mul_f32_e32 v108, 0xbfb8aa3b, v108
	v_exp_f32_e32 v105, v105
	v_exp_f32_e32 v108, v108
	v_add_f32_e32 v105, 1.0, v105
	v_add_f32_e32 v108, 1.0, v108
	v_rcp_f32_e32 v105, v105
	v_rcp_f32_e32 v108, v108
	v_mul_f32_e32 v105, v110, v105
	v_mul_f32_e32 v108, v111, v108
	v_cvt_pk_bf16_f32 v105, v105, v108
	v_mul_f32_e32 v108, 0x3d922279, v106
	v_fmaak_f32 v108, v106, v108, 0x3fcc422a
	v_mul_f32_e32 v108, v106, v108
	v_mul_f32_e32 v108, 0xbfb8aa3b, v108
	v_exp_f32_e32 v108, v108
	s_nop 0
	v_add_f32_e32 v108, 1.0, v108
	v_rcp_f32_e32 v108, v108
	s_nop 0
	v_mul_f32_e32 v106, v106, v108
	v_mul_f32_e32 v108, 0x3d922279, v107
	v_fmaak_f32 v108, v107, v108, 0x3fcc422a
	v_mul_f32_e32 v108, v107, v108
	v_mul_f32_e32 v108, 0xbfb8aa3b, v108
	v_exp_f32_e32 v108, v108
	s_nop 0
	v_add_f32_e32 v108, 1.0, v108
	v_rcp_f32_e32 v108, v108
	s_nop 0
	v_mul_f32_e32 v107, v107, v108
	v_cvt_pk_bf16_f32 v106, v106, v107
	v_mul_f32_e32 v107, 0x3d922279, v116
	v_mul_f32_e32 v108, 0x3d922279, v117
	v_fmaak_f32 v107, v116, v107, 0x3fcc422a
	v_fmaak_f32 v108, v117, v108, 0x3fcc422a
	v_mul_f32_e32 v107, v116, v107
	v_mul_f32_e32 v108, v117, v108
	v_mul_f32_e32 v107, 0xbfb8aa3b, v107
	v_mul_f32_e32 v108, 0xbfb8aa3b, v108
	v_exp_f32_e32 v107, v107
	v_exp_f32_e32 v108, v108
	v_add_f32_e32 v107, 1.0, v107
	v_add_f32_e32 v108, 1.0, v108
	v_rcp_f32_e32 v107, v107
	v_rcp_f32_e32 v108, v108
	v_mul_f32_e32 v107, v116, v107
	v_mul_f32_e32 v108, v117, v108
	v_cvt_pk_bf16_f32 v107, v107, v108
	v_lshl_add_u64 v[108:109], s[2:3], 0, v[112:113]
	v_lshl_add_u64 v[108:109], v[108:109], 0, v[142:143]
	global_store_dwordx4 v[108:109], v[104:107], off
	s_nop 1
	v_pk_fma_f32 v[104:105], v[98:99], v[114:115], v[34:35] op_sel_hi:[1,0,1]
	v_pk_fma_f32 v[98:99], v[96:97], v[114:115], v[32:33] op_sel_hi:[1,0,1]
	v_mul_f32_e32 v96, 0x3d922279, v100
	v_mul_f32_e32 v97, 0x3d922279, v101
	v_fmaak_f32 v96, v100, v96, 0x3fcc422a
	v_fmaak_f32 v97, v101, v97, 0x3fcc422a
	v_mul_f32_e32 v96, v100, v96
	v_mul_f32_e32 v97, v101, v97
	v_mul_f32_e32 v96, 0xbfb8aa3b, v96
	v_mul_f32_e32 v97, 0xbfb8aa3b, v97
	v_exp_f32_e32 v96, v96
	v_exp_f32_e32 v97, v97
	v_add_f32_e32 v96, 1.0, v96
	v_add_f32_e32 v97, 1.0, v97
	v_rcp_f32_e32 v96, v96
	v_rcp_f32_e32 v97, v97
	v_mul_f32_e32 v96, v100, v96
	v_mul_f32_e32 v97, v101, v97
	v_cvt_pk_bf16_f32 v96, v96, v97
	v_mul_f32_e32 v97, 0x3d922279, v102
	v_mul_f32_e32 v100, 0x3d922279, v103
	v_fmaak_f32 v97, v102, v97, 0x3fcc422a
	v_fmaak_f32 v100, v103, v100, 0x3fcc422a
	v_mul_f32_e32 v97, v102, v97
	v_mul_f32_e32 v100, v103, v100
	v_mul_f32_e32 v97, 0xbfb8aa3b, v97
	v_mul_f32_e32 v100, 0xbfb8aa3b, v100
	v_exp_f32_e32 v97, v97
	v_exp_f32_e32 v100, v100
	v_add_f32_e32 v97, 1.0, v97
; __device__ __forceinline__ unsigned pk2(float lo, float hi) { unsigned r; asm volatile("v_cvt_pk_bf16_f32 %0, %1, %2" : "=v"(r) : "v"(lo), "v"(hi)); return r; }
; __device__ __forceinline__ float rstd_of(float ss) { return __builtin_amdgcn_rsqf(ss * (1.0f / 1024.0f) + EPS); }
; __device__ __forceinline__ float gelu_tanh_f(float v) {
;     const float z2 = v * (1.5957691216057308f + 0.07135481627159493f * v * v);
;     return v * __builtin_amdgcn_rcpf(1.0f + __builtin_amdgcn_exp2f(-1.4426950408889634f * z2));
; }
;     __device__ __forceinline__ void operator()(const f32x4 (&acc)[2][2][4][2], const Unit& u, int wr, int wc, int fr_, int fq_) const {
;     ...
;         for (int ai = 0; ai < 2; ++ai)
; #pragma unroll
;             for (int m = 0; m < 4; ++m) {
;                 const int r = row0 + ai * 128 + m * 16; const float rs = rstd_of(rowss[r]);
; #pragma unroll
;                 for (int bj = 0; bj < 2; ++bj) {
;                     const f32x4 v0 = acc[ai][bj][m][0] * rs + bv[bj][0], v1 = acc[ai][bj][m][1] * rs + bv[bj][1];
;                     u32x4 w; w.x = pk2(gelu_tanh_f(v0[0]), gelu_tanh_f(v0[1])); w.y = pk2(gelu_tanh_f(v0[2]), gelu_tanh_f(v0[3]));
;                     w.z = pk2(gelu_tanh_f(v1[0]), gelu_tanh_f(v1[1])); w.w = pk2(gelu_tanh_f(v1[2]), gelu_tanh_f(v1[3]));
;                     *(u32x4*)(O + (size_t)r * 1024 + col0 + bj * 128) = w;
	v_add_f32_e32 v100, 1.0, v100
	v_rcp_f32_e32 v97, v97
	v_rcp_f32_e32 v100, v100
	v_mul_f32_e32 v97, v102, v97
	v_mul_f32_e32 v100, v103, v100
	v_cvt_pk_bf16_f32 v97, v97, v100
	v_mul_f32_e32 v100, 0x3d922279, v98
	v_fmaak_f32 v100, v98, v100, 0x3fcc422a
	v_mul_f32_e32 v100, v98, v100
	v_mul_f32_e32 v100, 0xbfb8aa3b, v100
	v_exp_f32_e32 v100, v100
	s_nop 0
	v_add_f32_e32 v100, 1.0, v100
	v_rcp_f32_e32 v100, v100
	s_nop 0
	v_mul_f32_e32 v98, v98, v100
	v_mul_f32_e32 v100, 0x3d922279, v99
	v_fmaak_f32 v100, v99, v100, 0x3fcc422a
	v_mul_f32_e32 v100, v99, v100
	v_mul_f32_e32 v100, 0xbfb8aa3b, v100
	v_exp_f32_e32 v100, v100
	s_nop 0
	v_add_f32_e32 v100, 1.0, v100
	v_rcp_f32_e32 v100, v100
	s_nop 0
	v_mul_f32_e32 v99, v99, v100
	v_cvt_pk_bf16_f32 v98, v98, v99
	v_mul_f32_e32 v99, 0x3d922279, v104
	v_fmaak_f32 v99, v104, v99, 0x3fcc422a
	v_mul_f32_e32 v100, 0x3d922279, v105
	v_mul_f32_e32 v99, v104, v99
	v_fmaak_f32 v100, v105, v100, 0x3fcc422a
	v_mul_f32_e32 v99, 0xbfb8aa3b, v99
	v_mul_f32_e32 v100, v105, v100
	v_exp_f32_e32 v99, v99
	v_mul_f32_e32 v100, 0xbfb8aa3b, v100
	v_exp_f32_e32 v100, v100
	v_add_f32_e32 v99, 1.0, v99
	v_rcp_f32_e32 v99, v99
	v_add_f32_e32 v100, 1.0, v100
	v_rcp_f32_e32 v100, v100
	v_mul_f32_e32 v99, v104, v99
	v_mul_f32_e32 v100, v105, v100
	v_cvt_pk_bf16_f32 v99, v99, v100
	global_store_dwordx4 v[108:109], v[96:99], off offset:256
	s_nop 1
	v_mov_b32_e32 v98, v180
	s_nop 0
	v_or_b32_e32 v96, 48, v156
	v_ashrrev_i32_e32 v97, 31, v96
	v_lshlrev_b64 v[96:97], 11, v[96:97]
	v_fmamk_f32 v98, v98, 0x3a800000, v213
	v_rsq_f32_e32 v98, v98
	s_nop 0
	v_pk_fma_f32 v[92:93], v[92:93], v[98:99], v[52:53] op_sel_hi:[1,0,1]
	v_pk_fma_f32 v[100:101], v[90:91], v[98:99], v[50:51] op_sel_hi:[1,0,1]
	v_pk_fma_f32 v[90:91], v[88:89], v[98:99], v[48:49] op_sel_hi:[1,0,1]
	v_mul_f32_e32 v88, 0x3d922279, v92
	v_mul_f32_e32 v89, 0x3d922279, v93
	v_fmaak_f32 v88, v92, v88, 0x3fcc422a
	v_fmaak_f32 v89, v93, v89, 0x3fcc422a
	v_mul_f32_e32 v88, v92, v88
	v_mul_f32_e32 v89, v93, v89
	v_mul_f32_e32 v88, 0xbfb8aa3b, v88
	v_mul_f32_e32 v89, 0xbfb8aa3b, v89
	v_exp_f32_e32 v88, v88
	v_exp_f32_e32 v89, v89
	v_pk_fma_f32 v[94:95], v[94:95], v[98:99], v[54:55] op_sel_hi:[1,0,1]
	v_pk_fma_f32 v[84:85], v[84:85], v[98:99], v[36:37] op_sel_hi:[1,0,1]
	v_add_f32_e32 v88, 1.0, v88
	v_add_f32_e32 v89, 1.0, v89
	v_rcp_f32_e32 v88, v88
	v_rcp_f32_e32 v89, v89
	v_pk_fma_f32 v[86:87], v[86:87], v[98:99], v[38:39] op_sel_hi:[1,0,1]
	v_mul_f32_e32 v88, v92, v88
	v_mul_f32_e32 v89, v93, v89
	v_cvt_pk_bf16_f32 v88, v88, v89
	v_mul_f32_e32 v89, 0x3d922279, v94
	v_mul_f32_e32 v92, 0x3d922279, v95
	v_fmaak_f32 v89, v94, v89, 0x3fcc422a
	v_fmaak_f32 v92, v95, v92, 0x3fcc422a
	v_mul_f32_e32 v89, v94, v89
	v_mul_f32_e32 v92, v95, v92
	v_mul_f32_e32 v89, 0xbfb8aa3b, v89
	v_mul_f32_e32 v92, 0xbfb8aa3b, v92
	v_exp_f32_e32 v89, v89
	v_exp_f32_e32 v92, v92
	v_add_f32_e32 v89, 1.0, v89
	v_add_f32_e32 v92, 1.0, v92
	v_rcp_f32_e32 v89, v89
	v_rcp_f32_e32 v92, v92
	v_mul_f32_e32 v89, v94, v89
	v_mul_f32_e32 v92, v95, v92
	v_cvt_pk_bf16_f32 v89, v89, v92
	v_mul_f32_e32 v92, 0x3d922279, v90
	v_fmaak_f32 v92, v90, v92, 0x3fcc422a
	v_mul_f32_e32 v92, v90, v92
	v_mul_f32_e32 v92, 0xbfb8aa3b, v92
	v_exp_f32_e32 v92, v92
	s_nop 0
	v_add_f32_e32 v92, 1.0, v92
	v_rcp_f32_e32 v92, v92
	s_nop 0
	v_mul_f32_e32 v90, v90, v92
	v_mul_f32_e32 v92, 0x3d922279, v91
	v_fmaak_f32 v92, v91, v92, 0x3fcc422a
	v_mul_f32_e32 v92, v91, v92
	v_mul_f32_e32 v92, 0xbfb8aa3b, v92
	v_exp_f32_e32 v92, v92
	s_nop 0
	v_add_f32_e32 v92, 1.0, v92
	v_rcp_f32_e32 v92, v92
	s_nop 0
	v_mul_f32_e32 v91, v91, v92
	v_cvt_pk_bf16_f32 v90, v90, v91
	v_mul_f32_e32 v91, 0x3d922279, v100
	v_mul_f32_e32 v92, 0x3d922279, v101
	v_fmaak_f32 v91, v100, v91, 0x3fcc422a
	v_fmaak_f32 v92, v101, v92, 0x3fcc422a
	v_mul_f32_e32 v91, v100, v91
	v_mul_f32_e32 v92, v101, v92
	v_mul_f32_e32 v91, 0xbfb8aa3b, v91
	v_mul_f32_e32 v92, 0xbfb8aa3b, v92
	v_exp_f32_e32 v91, v91
	v_exp_f32_e32 v92, v92
	v_add_f32_e32 v91, 1.0, v91
	v_add_f32_e32 v92, 1.0, v92
	v_rcp_f32_e32 v91, v91
	v_rcp_f32_e32 v92, v92
	v_mul_f32_e32 v91, v100, v91
	v_mul_f32_e32 v92, v101, v92
	v_cvt_pk_bf16_f32 v91, v91, v92
	v_lshl_add_u64 v[92:93], s[2:3], 0, v[96:97]
	v_lshl_add_u64 v[92:93], v[92:93], 0, v[142:143]
	global_store_dwordx4 v[92:93], v[88:91], off
	s_mov_b32 s2, 0x40000
	s_nop 0
	v_pk_fma_f32 v[88:89], v[82:83], v[98:99], v[34:35] op_sel_hi:[1,0,1]
	v_pk_fma_f32 v[82:83], v[80:81], v[98:99], v[32:33] op_sel_hi:[1,0,1]
	v_mul_f32_e32 v80, 0x3d922279, v84
	v_mul_f32_e32 v81, 0x3d922279, v85
	v_fmaak_f32 v80, v84, v80, 0x3fcc422a
	v_fmaak_f32 v81, v85, v81, 0x3fcc422a
	v_mul_f32_e32 v80, v84, v80
	v_mul_f32_e32 v81, v85, v81
	v_mul_f32_e32 v80, 0xbfb8aa3b, v80
	v_mul_f32_e32 v81, 0xbfb8aa3b, v81
	v_exp_f32_e32 v80, v80
	v_exp_f32_e32 v81, v81
	v_add_f32_e32 v80, 1.0, v80
	v_add_f32_e32 v81, 1.0, v81
	v_rcp_f32_e32 v80, v80
	v_rcp_f32_e32 v81, v81
	v_mul_f32_e32 v80, v84, v80
	v_mul_f32_e32 v81, v85, v81
	v_cvt_pk_bf16_f32 v80, v80, v81
	v_mul_f32_e32 v81, 0x3d922279, v86
	v_mul_f32_e32 v84, 0x3d922279, v87
	v_fmaak_f32 v81, v86, v81, 0x3fcc422a
	v_fmaak_f32 v84, v87, v84, 0x3fcc422a
	v_mul_f32_e32 v81, v86, v81
	v_mul_f32_e32 v84, v87, v84
	v_mul_f32_e32 v81, 0xbfb8aa3b, v81
	v_mul_f32_e32 v84, 0xbfb8aa3b, v84
	v_exp_f32_e32 v81, v81
	v_exp_f32_e32 v84, v84
	v_add_f32_e32 v81, 1.0, v81
	v_add_f32_e32 v84, 1.0, v84
	v_rcp_f32_e32 v81, v81
	v_rcp_f32_e32 v84, v84
	v_mul_f32_e32 v81, v86, v81
	v_mul_f32_e32 v84, v87, v84
	v_cvt_pk_bf16_f32 v81, v81, v84
	v_mul_f32_e32 v84, 0x3d922279, v82
	v_fmaak_f32 v84, v82, v84, 0x3fcc422a
	v_mul_f32_e32 v84, v82, v84
; __device__ __forceinline__ unsigned pk2(float lo, float hi) { unsigned r; asm volatile("v_cvt_pk_bf16_f32 %0, %1, %2" : "=v"(r) : "v"(lo), "v"(hi)); return r; }
; __device__ __forceinline__ float rstd_of(float ss) { return __builtin_amdgcn_rsqf(ss * (1.0f / 1024.0f) + EPS); }
; __device__ __forceinline__ float gelu_tanh_f(float v) {
;     const float z2 = v * (1.5957691216057308f + 0.07135481627159493f * v * v);
;     return v * __builtin_amdgcn_rcpf(1.0f + __builtin_amdgcn_exp2f(-1.4426950408889634f * z2));
; }
;     __device__ __forceinline__ void operator()(const f32x4 (&acc)[2][2][4][2], const Unit& u, int wr, int wc, int fr_, int fq_) const {
;     ...
;         for (int ai = 0; ai < 2; ++ai)
; #pragma unroll
;             for (int m = 0; m < 4; ++m) {
;                 const int r = row0 + ai * 128 + m * 16; const float rs = rstd_of(rowss[r]);
; #pragma unroll
;                 for (int bj = 0; bj < 2; ++bj) {
;                     const f32x4 v0 = acc[ai][bj][m][0] * rs + bv[bj][0], v1 = acc[ai][bj][m][1] * rs + bv[bj][1];
;                     u32x4 w; w.x = pk2(gelu_tanh_f(v0[0]), gelu_tanh_f(v0[1])); w.y = pk2(gelu_tanh_f(v0[2]), gelu_tanh_f(v0[3]));
;                     w.z = pk2(gelu_tanh_f(v1[0]), gelu_tanh_f(v1[1])); w.w = pk2(gelu_tanh_f(v1[2]), gelu_tanh_f(v1[3]));
;                     *(u32x4*)(O + (size_t)r * 1024 + col0 + bj * 128) = w;
	v_mul_f32_e32 v84, 0xbfb8aa3b, v84
	v_exp_f32_e32 v84, v84
	s_nop 0
	v_add_f32_e32 v84, 1.0, v84
	v_rcp_f32_e32 v84, v84
	s_nop 0
	v_mul_f32_e32 v82, v82, v84
	v_mul_f32_e32 v84, 0x3d922279, v83
	v_fmaak_f32 v84, v83, v84, 0x3fcc422a
	v_mul_f32_e32 v84, v83, v84
	v_mul_f32_e32 v84, 0xbfb8aa3b, v84
	v_exp_f32_e32 v84, v84
	s_nop 0
	v_add_f32_e32 v84, 1.0, v84
	v_rcp_f32_e32 v84, v84
	s_nop 0
	v_mul_f32_e32 v83, v83, v84
	v_cvt_pk_bf16_f32 v82, v82, v83
	v_mul_f32_e32 v83, 0x3d922279, v88
	v_fmaak_f32 v83, v88, v83, 0x3fcc422a
	v_mul_f32_e32 v84, 0x3d922279, v89
	v_mul_f32_e32 v83, v88, v83
	v_fmaak_f32 v84, v89, v84, 0x3fcc422a
	v_mul_f32_e32 v83, 0xbfb8aa3b, v83
	v_mul_f32_e32 v84, v89, v84
	v_exp_f32_e32 v83, v83
	v_mul_f32_e32 v84, 0xbfb8aa3b, v84
	v_exp_f32_e32 v84, v84
	v_add_f32_e32 v83, 1.0, v83
	v_rcp_f32_e32 v83, v83
	v_add_f32_e32 v84, 1.0, v84
	v_rcp_f32_e32 v84, v84
	v_mul_f32_e32 v83, v88, v83
	v_mul_f32_e32 v84, v89, v84
	v_cvt_pk_bf16_f32 v83, v83, v84
	global_store_dwordx4 v[92:93], v[80:83], off offset:256
	s_nop 1
	v_mov_b32_e32 v80, v181
	v_fmamk_f32 v80, v80, 0x3a800000, v213
	v_rsq_f32_e32 v80, v80
	s_nop 0
	v_pk_fma_f32 v[76:77], v[76:77], v[80:81], v[52:53] op_sel_hi:[1,0,1]
	v_pk_fma_f32 v[82:83], v[74:75], v[80:81], v[50:51] op_sel_hi:[1,0,1]
	v_pk_fma_f32 v[74:75], v[72:73], v[80:81], v[48:49] op_sel_hi:[1,0,1]
	v_mul_f32_e32 v72, 0x3d922279, v76
	v_mul_f32_e32 v73, 0x3d922279, v77
	v_fmaak_f32 v72, v76, v72, 0x3fcc422a
	v_fmaak_f32 v73, v77, v73, 0x3fcc422a
	v_mul_f32_e32 v72, v76, v72
	v_mul_f32_e32 v73, v77, v73
	v_mul_f32_e32 v72, 0xbfb8aa3b, v72
	v_mul_f32_e32 v73, 0xbfb8aa3b, v73
	v_exp_f32_e32 v72, v72
	v_exp_f32_e32 v73, v73
	v_pk_fma_f32 v[78:79], v[78:79], v[80:81], v[54:55] op_sel_hi:[1,0,1]
	v_pk_fma_f32 v[68:69], v[68:69], v[80:81], v[36:37] op_sel_hi:[1,0,1]
	v_add_f32_e32 v72, 1.0, v72
	v_add_f32_e32 v73, 1.0, v73
	v_rcp_f32_e32 v72, v72
	v_rcp_f32_e32 v73, v73
	v_pk_fma_f32 v[70:71], v[70:71], v[80:81], v[38:39] op_sel_hi:[1,0,1]
	v_mul_f32_e32 v72, v76, v72
	v_mul_f32_e32 v73, v77, v73
	v_cvt_pk_bf16_f32 v72, v72, v73
	v_mul_f32_e32 v73, 0x3d922279, v78
	v_mul_f32_e32 v76, 0x3d922279, v79
	v_fmaak_f32 v73, v78, v73, 0x3fcc422a
	v_fmaak_f32 v76, v79, v76, 0x3fcc422a
	v_mul_f32_e32 v73, v78, v73
	v_mul_f32_e32 v76, v79, v76
	v_mul_f32_e32 v73, 0xbfb8aa3b, v73
	v_mul_f32_e32 v76, 0xbfb8aa3b, v76
	v_exp_f32_e32 v73, v73
	v_exp_f32_e32 v76, v76
	v_add_f32_e32 v73, 1.0, v73
	v_add_f32_e32 v76, 1.0, v76
	v_rcp_f32_e32 v73, v73
	v_rcp_f32_e32 v76, v76
	v_mul_f32_e32 v73, v78, v73
	v_mul_f32_e32 v76, v79, v76
	v_cvt_pk_bf16_f32 v73, v73, v76
	v_mul_f32_e32 v76, 0x3d922279, v74
	v_fmaak_f32 v76, v74, v76, 0x3fcc422a
	v_mul_f32_e32 v76, v74, v76
	v_mul_f32_e32 v76, 0xbfb8aa3b, v76
	v_exp_f32_e32 v76, v76
	v_add_co_u32_e32 v78, vcc, s2, v140
	s_mov_b32 s2, 0x50000
	v_add_f32_e32 v76, 1.0, v76
	v_rcp_f32_e32 v76, v76
	v_addc_co_u32_e32 v79, vcc, 0, v141, vcc
	v_mul_f32_e32 v74, v74, v76
	v_mul_f32_e32 v76, 0x3d922279, v75
	v_fmaak_f32 v76, v75, v76, 0x3fcc422a
	v_mul_f32_e32 v76, v75, v76
	v_mul_f32_e32 v76, 0xbfb8aa3b, v76
	v_exp_f32_e32 v76, v76
	s_nop 0
	v_add_f32_e32 v76, 1.0, v76
	v_rcp_f32_e32 v76, v76
	s_nop 0
	v_mul_f32_e32 v75, v75, v76
	v_cvt_pk_bf16_f32 v74, v74, v75
	v_mul_f32_e32 v75, 0x3d922279, v82
	v_fmaak_f32 v75, v82, v75, 0x3fcc422a
	v_mul_f32_e32 v76, 0x3d922279, v83
	v_mul_f32_e32 v75, v82, v75
	v_fmaak_f32 v76, v83, v76, 0x3fcc422a
	v_mul_f32_e32 v75, 0xbfb8aa3b, v75
	v_mul_f32_e32 v76, v83, v76
	v_exp_f32_e32 v75, v75
	v_mul_f32_e32 v76, 0xbfb8aa3b, v76
	v_exp_f32_e32 v76, v76
	v_add_f32_e32 v75, 1.0, v75
	v_rcp_f32_e32 v75, v75
	v_add_f32_e32 v76, 1.0, v76
	v_rcp_f32_e32 v76, v76
	v_mul_f32_e32 v75, v82, v75
	v_mul_f32_e32 v76, v83, v76
	v_cvt_pk_bf16_f32 v75, v75, v76
	global_store_dwordx4 v[78:79], v[72:75], off
	v_lshl_add_u64 v[76:77], v[140:141], 0, s[28:29]
	s_mov_b64 s[28:29], 0x48000
	v_pk_fma_f32 v[72:73], v[66:67], v[80:81], v[34:35] op_sel_hi:[1,0,1]
	v_pk_fma_f32 v[66:67], v[64:65], v[80:81], v[32:33] op_sel_hi:[1,0,1]
	v_mul_f32_e32 v64, 0x3d922279, v68
	v_mul_f32_e32 v65, 0x3d922279, v69
	v_fmaak_f32 v64, v68, v64, 0x3fcc422a
	v_fmaak_f32 v65, v69, v65, 0x3fcc422a
	v_mul_f32_e32 v64, v68, v64
	v_mul_f32_e32 v65, v69, v65
	v_mul_f32_e32 v64, 0xbfb8aa3b, v64
	v_mul_f32_e32 v65, 0xbfb8aa3b, v65
	v_exp_f32_e32 v64, v64
	v_exp_f32_e32 v65, v65
	v_add_f32_e32 v64, 1.0, v64
	v_add_f32_e32 v65, 1.0, v65
	v_rcp_f32_e32 v64, v64
	v_rcp_f32_e32 v65, v65
	v_mul_f32_e32 v64, v68, v64
	v_mul_f32_e32 v65, v69, v65
	v_cvt_pk_bf16_f32 v64, v64, v65
	v_mul_f32_e32 v65, 0x3d922279, v70
	v_mul_f32_e32 v68, 0x3d922279, v71
	v_fmaak_f32 v65, v70, v65, 0x3fcc422a
	v_fmaak_f32 v68, v71, v68, 0x3fcc422a
	v_mul_f32_e32 v65, v70, v65
	v_mul_f32_e32 v68, v71, v68
	v_mul_f32_e32 v65, 0xbfb8aa3b, v65
	v_mul_f32_e32 v68, 0xbfb8aa3b, v68
	v_exp_f32_e32 v65, v65
	v_exp_f32_e32 v68, v68
	v_add_f32_e32 v65, 1.0, v65
	v_add_f32_e32 v68, 1.0, v68
	v_rcp_f32_e32 v65, v65
	v_rcp_f32_e32 v68, v68
	v_mul_f32_e32 v65, v70, v65
	v_mul_f32_e32 v68, v71, v68
	v_cvt_pk_bf16_f32 v65, v65, v68
	v_mul_f32_e32 v68, 0x3d922279, v66
	v_fmaak_f32 v68, v66, v68, 0x3fcc422a
	v_mul_f32_e32 v68, v66, v68
	v_mul_f32_e32 v68, 0xbfb8aa3b, v68
	v_exp_f32_e32 v68, v68
	s_nop 0
	v_add_f32_e32 v68, 1.0, v68
	v_rcp_f32_e32 v68, v68
	s_nop 0
	v_mul_f32_e32 v66, v66, v68
	v_mul_f32_e32 v68, 0x3d922279, v67
	v_fmaak_f32 v68, v67, v68, 0x3fcc422a
	v_mul_f32_e32 v68, v67, v68
	v_mul_f32_e32 v68, 0xbfb8aa3b, v68
	v_exp_f32_e32 v68, v68
	s_nop 0
	v_add_f32_e32 v68, 1.0, v68
	v_rcp_f32_e32 v68, v68
	s_nop 0
	v_mul_f32_e32 v67, v67, v68
; __device__ __forceinline__ unsigned pk2(float lo, float hi) { unsigned r; asm volatile("v_cvt_pk_bf16_f32 %0, %1, %2" : "=v"(r) : "v"(lo), "v"(hi)); return r; }
; __device__ __forceinline__ float rstd_of(float ss) { return __builtin_amdgcn_rsqf(ss * (1.0f / 1024.0f) + EPS); }
; __device__ __forceinline__ float gelu_tanh_f(float v) {
;     const float z2 = v * (1.5957691216057308f + 0.07135481627159493f * v * v);
;     return v * __builtin_amdgcn_rcpf(1.0f + __builtin_amdgcn_exp2f(-1.4426950408889634f * z2));
; }
;     __device__ __forceinline__ void operator()(const f32x4 (&acc)[2][2][4][2], const Unit& u, int wr, int wc, int fr_, int fq_) const {
;     ...
;         for (int ai = 0; ai < 2; ++ai)
; #pragma unroll
;             for (int m = 0; m < 4; ++m) {
;                 const int r = row0 + ai * 128 + m * 16; const float rs = rstd_of(rowss[r]);
; #pragma unroll
;                 for (int bj = 0; bj < 2; ++bj) {
;                     const f32x4 v0 = acc[ai][bj][m][0] * rs + bv[bj][0], v1 = acc[ai][bj][m][1] * rs + bv[bj][1];
;                     u32x4 w; w.x = pk2(gelu_tanh_f(v0[0]), gelu_tanh_f(v0[1])); w.y = pk2(gelu_tanh_f(v0[2]), gelu_tanh_f(v0[3]));
;                     w.z = pk2(gelu_tanh_f(v1[0]), gelu_tanh_f(v1[1])); w.w = pk2(gelu_tanh_f(v1[2]), gelu_tanh_f(v1[3]));
;                     *(u32x4*)(O + (size_t)r * 1024 + col0 + bj * 128) = w;
	v_cvt_pk_bf16_f32 v66, v66, v67
	v_mul_f32_e32 v67, 0x3d922279, v72
	v_fmaak_f32 v67, v72, v67, 0x3fcc422a
	v_mul_f32_e32 v68, 0x3d922279, v73
	v_mul_f32_e32 v67, v72, v67
	v_fmaak_f32 v68, v73, v68, 0x3fcc422a
	v_mul_f32_e32 v67, 0xbfb8aa3b, v67
	v_mul_f32_e32 v68, v73, v68
	v_exp_f32_e32 v67, v67
	v_mul_f32_e32 v68, 0xbfb8aa3b, v68
	v_exp_f32_e32 v68, v68
	v_add_f32_e32 v67, 1.0, v67
	v_rcp_f32_e32 v67, v67
	v_add_f32_e32 v68, 1.0, v68
	v_rcp_f32_e32 v68, v68
	v_mul_f32_e32 v67, v72, v67
	v_mul_f32_e32 v68, v73, v68
	v_cvt_pk_bf16_f32 v67, v67, v68
	global_store_dwordx4 v[76:77], v[64:67], off offset:256
	s_nop 1
	v_mov_b32_e32 v64, v182
	v_fmamk_f32 v64, v64, 0x3a800000, v213
	v_rsq_f32_e32 v64, v64
	s_nop 0
	v_pk_fma_f32 v[60:61], v[60:61], v[64:65], v[52:53] op_sel_hi:[1,0,1]
	v_pk_fma_f32 v[66:67], v[58:59], v[64:65], v[50:51] op_sel_hi:[1,0,1]
	v_pk_fma_f32 v[58:59], v[56:57], v[64:65], v[48:49] op_sel_hi:[1,0,1]
	v_mul_f32_e32 v56, 0x3d922279, v60
	v_mul_f32_e32 v57, 0x3d922279, v61
	v_fmaak_f32 v56, v60, v56, 0x3fcc422a
	v_fmaak_f32 v57, v61, v57, 0x3fcc422a
	v_mul_f32_e32 v56, v60, v56
	v_mul_f32_e32 v57, v61, v57
	v_mul_f32_e32 v56, 0xbfb8aa3b, v56
	v_mul_f32_e32 v57, 0xbfb8aa3b, v57
	v_exp_f32_e32 v56, v56
	v_exp_f32_e32 v57, v57
	v_pk_fma_f32 v[62:63], v[62:63], v[64:65], v[54:55] op_sel_hi:[1,0,1]
	v_pk_fma_f32 v[44:45], v[44:45], v[64:65], v[36:37] op_sel_hi:[1,0,1]
	v_add_f32_e32 v56, 1.0, v56
	v_add_f32_e32 v57, 1.0, v57
	v_rcp_f32_e32 v56, v56
	v_rcp_f32_e32 v57, v57
	v_pk_fma_f32 v[46:47], v[46:47], v[64:65], v[38:39] op_sel_hi:[1,0,1]
	v_mul_f32_e32 v56, v60, v56
	v_mul_f32_e32 v57, v61, v57
	v_cvt_pk_bf16_f32 v56, v56, v57
	v_mul_f32_e32 v57, 0x3d922279, v62
	v_mul_f32_e32 v60, 0x3d922279, v63
	v_fmaak_f32 v57, v62, v57, 0x3fcc422a
	v_fmaak_f32 v60, v63, v60, 0x3fcc422a
	v_mul_f32_e32 v57, v62, v57
	v_mul_f32_e32 v60, v63, v60
	v_mul_f32_e32 v57, 0xbfb8aa3b, v57
	v_mul_f32_e32 v60, 0xbfb8aa3b, v60
	v_exp_f32_e32 v57, v57
	v_exp_f32_e32 v60, v60
	v_add_f32_e32 v57, 1.0, v57
	v_add_f32_e32 v60, 1.0, v60
	v_rcp_f32_e32 v57, v57
	v_rcp_f32_e32 v60, v60
	v_mul_f32_e32 v57, v62, v57
	v_mul_f32_e32 v60, v63, v60
	v_cvt_pk_bf16_f32 v57, v57, v60
	v_mul_f32_e32 v60, 0x3d922279, v58
	v_fmaak_f32 v60, v58, v60, 0x3fcc422a
	v_mul_f32_e32 v60, v58, v60
	v_mul_f32_e32 v60, 0xbfb8aa3b, v60
	v_exp_f32_e32 v60, v60
	v_add_co_u32_e32 v62, vcc, s33, v140
	v_add_f32_e32 v60, 1.0, v60
	v_rcp_f32_e32 v60, v60
	v_addc_co_u32_e32 v63, vcc, 0, v141, vcc
	v_mul_f32_e32 v58, v58, v60
	v_mul_f32_e32 v60, 0x3d922279, v59
	v_fmaak_f32 v60, v59, v60, 0x3fcc422a
	v_mul_f32_e32 v60, v59, v60
	v_mul_f32_e32 v60, 0xbfb8aa3b, v60
	v_exp_f32_e32 v60, v60
	s_nop 0
	v_add_f32_e32 v60, 1.0, v60
	v_rcp_f32_e32 v60, v60
	s_nop 0
	v_mul_f32_e32 v59, v59, v60
	v_cvt_pk_bf16_f32 v58, v58, v59
	v_mul_f32_e32 v59, 0x3d922279, v66
	v_fmaak_f32 v59, v66, v59, 0x3fcc422a
	v_mul_f32_e32 v60, 0x3d922279, v67
	v_mul_f32_e32 v59, v66, v59
	v_fmaak_f32 v60, v67, v60, 0x3fcc422a
	v_mul_f32_e32 v59, 0xbfb8aa3b, v59
	v_mul_f32_e32 v60, v67, v60
	v_exp_f32_e32 v59, v59
	v_mul_f32_e32 v60, 0xbfb8aa3b, v60
	v_exp_f32_e32 v60, v60
	v_add_f32_e32 v59, 1.0, v59
	v_rcp_f32_e32 v59, v59
	v_add_f32_e32 v60, 1.0, v60
	v_rcp_f32_e32 v60, v60
	v_mul_f32_e32 v59, v66, v59
	v_mul_f32_e32 v60, v67, v60
	v_cvt_pk_bf16_f32 v59, v59, v60
	global_store_dwordx4 v[62:63], v[56:59], off
	v_lshl_add_u64 v[60:61], v[140:141], 0, s[28:29]
	s_mov_b64 s[28:29], 0x50000
	v_pk_fma_f32 v[56:57], v[42:43], v[64:65], v[34:35] op_sel_hi:[1,0,1]
	v_pk_fma_f32 v[42:43], v[40:41], v[64:65], v[32:33] op_sel_hi:[1,0,1]
	v_mul_f32_e32 v40, 0x3d922279, v44
	v_mul_f32_e32 v41, 0x3d922279, v45
	v_fmaak_f32 v40, v44, v40, 0x3fcc422a
	v_fmaak_f32 v41, v45, v41, 0x3fcc422a
	v_mul_f32_e32 v40, v44, v40
	v_mul_f32_e32 v41, v45, v41
	v_mul_f32_e32 v40, 0xbfb8aa3b, v40
	v_mul_f32_e32 v41, 0xbfb8aa3b, v41
	v_exp_f32_e32 v40, v40
	v_exp_f32_e32 v41, v41
	v_add_f32_e32 v40, 1.0, v40
	v_add_f32_e32 v41, 1.0, v41
	v_rcp_f32_e32 v40, v40
	v_rcp_f32_e32 v41, v41
	v_mul_f32_e32 v40, v44, v40
	v_mul_f32_e32 v41, v45, v41
	v_cvt_pk_bf16_f32 v40, v40, v41
	v_mul_f32_e32 v41, 0x3d922279, v46
	v_mul_f32_e32 v44, 0x3d922279, v47
	v_fmaak_f32 v41, v46, v41, 0x3fcc422a
	v_fmaak_f32 v44, v47, v44, 0x3fcc422a
	v_mul_f32_e32 v41, v46, v41
	v_mul_f32_e32 v44, v47, v44
	v_mul_f32_e32 v41, 0xbfb8aa3b, v41
	v_mul_f32_e32 v44, 0xbfb8aa3b, v44
	v_exp_f32_e32 v41, v41
	v_exp_f32_e32 v44, v44
	v_add_f32_e32 v41, 1.0, v41
	v_add_f32_e32 v44, 1.0, v44
	v_rcp_f32_e32 v41, v41
	v_rcp_f32_e32 v44, v44
	v_mul_f32_e32 v41, v46, v41
	v_mul_f32_e32 v44, v47, v44
	v_cvt_pk_bf16_f32 v41, v41, v44
	v_mul_f32_e32 v44, 0x3d922279, v42
	v_fmaak_f32 v44, v42, v44, 0x3fcc422a
	v_mul_f32_e32 v44, v42, v44
	v_mul_f32_e32 v44, 0xbfb8aa3b, v44
	v_exp_f32_e32 v44, v44
	s_nop 0
	v_add_f32_e32 v44, 1.0, v44
	v_rcp_f32_e32 v44, v44
	s_nop 0
	v_mul_f32_e32 v42, v42, v44
	v_mul_f32_e32 v44, 0x3d922279, v43
	v_fmaak_f32 v44, v43, v44, 0x3fcc422a
	v_mul_f32_e32 v44, v43, v44
	v_mul_f32_e32 v44, 0xbfb8aa3b, v44
	v_exp_f32_e32 v44, v44
	s_nop 0
	v_add_f32_e32 v44, 1.0, v44
	v_rcp_f32_e32 v44, v44
	s_nop 0
	v_mul_f32_e32 v43, v43, v44
	v_cvt_pk_bf16_f32 v42, v42, v43
	v_mul_f32_e32 v43, 0x3d922279, v56
	v_fmaak_f32 v43, v56, v43, 0x3fcc422a
	v_mul_f32_e32 v44, 0x3d922279, v57
	v_mul_f32_e32 v43, v56, v43
	v_fmaak_f32 v44, v57, v44, 0x3fcc422a
	v_mul_f32_e32 v43, 0xbfb8aa3b, v43
	v_mul_f32_e32 v44, v57, v44
	v_exp_f32_e32 v43, v43
	v_mul_f32_e32 v44, 0xbfb8aa3b, v44
	v_exp_f32_e32 v44, v44
	v_add_f32_e32 v43, 1.0, v43
	v_rcp_f32_e32 v43, v43
	v_add_f32_e32 v44, 1.0, v44
; __device__ __forceinline__ unsigned pk2(float lo, float hi) { unsigned r; asm volatile("v_cvt_pk_bf16_f32 %0, %1, %2" : "=v"(r) : "v"(lo), "v"(hi)); return r; }
; __device__ __forceinline__ float rstd_of(float ss) { return __builtin_amdgcn_rsqf(ss * (1.0f / 1024.0f) + EPS); }
; __device__ __forceinline__ float gelu_tanh_f(float v) {
;     const float z2 = v * (1.5957691216057308f + 0.07135481627159493f * v * v);
;     return v * __builtin_amdgcn_rcpf(1.0f + __builtin_amdgcn_exp2f(-1.4426950408889634f * z2));
; }
;     __device__ __forceinline__ void operator()(const f32x4 (&acc)[2][2][4][2], const Unit& u, int wr, int wc, int fr_, int fq_) const {
;     ...
;         for (int ai = 0; ai < 2; ++ai)
; #pragma unroll
;             for (int m = 0; m < 4; ++m) {
;                 const int r = row0 + ai * 128 + m * 16; const float rs = rstd_of(rowss[r]);
; #pragma unroll
;                 for (int bj = 0; bj < 2; ++bj) {
;                     const f32x4 v0 = acc[ai][bj][m][0] * rs + bv[bj][0], v1 = acc[ai][bj][m][1] * rs + bv[bj][1];
;                     u32x4 w; w.x = pk2(gelu_tanh_f(v0[0]), gelu_tanh_f(v0[1])); w.y = pk2(gelu_tanh_f(v0[2]), gelu_tanh_f(v0[3]));
;                     w.z = pk2(gelu_tanh_f(v1[0]), gelu_tanh_f(v1[1])); w.w = pk2(gelu_tanh_f(v1[2]), gelu_tanh_f(v1[3]));
;                     *(u32x4*)(O + (size_t)r * 1024 + col0 + bj * 128) = w;
	v_rcp_f32_e32 v44, v44
	v_mul_f32_e32 v43, v56, v43
	v_mul_f32_e32 v44, v57, v44
	v_cvt_pk_bf16_f32 v43, v43, v44
	global_store_dwordx4 v[60:61], v[40:43], off offset:256
	s_nop 1
	v_mov_b32_e32 v40, v183
	v_fmamk_f32 v40, v40, 0x3a800000, v213
	v_rsq_f32_e32 v40, v40
	s_nop 0
	v_pk_fma_f32 v[28:29], v[28:29], v[40:41], v[52:53] op_sel_hi:[1,0,1]
	v_pk_fma_f32 v[42:43], v[26:27], v[40:41], v[50:51] op_sel_hi:[1,0,1]
	v_pk_fma_f32 v[26:27], v[24:25], v[40:41], v[48:49] op_sel_hi:[1,0,1]
	v_mul_f32_e32 v24, 0x3d922279, v28
	v_mul_f32_e32 v25, 0x3d922279, v29
	v_fmaak_f32 v24, v28, v24, 0x3fcc422a
	v_fmaak_f32 v25, v29, v25, 0x3fcc422a
	v_mul_f32_e32 v24, v28, v24
	v_mul_f32_e32 v25, v29, v25
	v_mul_f32_e32 v24, 0xbfb8aa3b, v24
	v_mul_f32_e32 v25, 0xbfb8aa3b, v25
	v_exp_f32_e32 v24, v24
	v_exp_f32_e32 v25, v25
	v_pk_fma_f32 v[30:31], v[30:31], v[40:41], v[54:55] op_sel_hi:[1,0,1]
	v_pk_fma_f32 v[20:21], v[20:21], v[40:41], v[36:37] op_sel_hi:[1,0,1]
	v_add_f32_e32 v24, 1.0, v24
	v_add_f32_e32 v25, 1.0, v25
	v_rcp_f32_e32 v24, v24
	v_rcp_f32_e32 v25, v25
	v_pk_fma_f32 v[22:23], v[22:23], v[40:41], v[38:39] op_sel_hi:[1,0,1]
	v_mul_f32_e32 v24, v28, v24
	v_mul_f32_e32 v25, v29, v25
	v_cvt_pk_bf16_f32 v24, v24, v25
	v_mul_f32_e32 v25, 0x3d922279, v30
	v_mul_f32_e32 v28, 0x3d922279, v31
	v_fmaak_f32 v25, v30, v25, 0x3fcc422a
	v_fmaak_f32 v28, v31, v28, 0x3fcc422a
	v_mul_f32_e32 v25, v30, v25
	v_mul_f32_e32 v28, v31, v28
	v_mul_f32_e32 v25, 0xbfb8aa3b, v25
	v_mul_f32_e32 v28, 0xbfb8aa3b, v28
	v_exp_f32_e32 v25, v25
	v_exp_f32_e32 v28, v28
	v_add_f32_e32 v25, 1.0, v25
	v_add_f32_e32 v28, 1.0, v28
	v_rcp_f32_e32 v25, v25
	v_rcp_f32_e32 v28, v28
	v_mul_f32_e32 v25, v30, v25
	v_mul_f32_e32 v28, v31, v28
	v_cvt_pk_bf16_f32 v25, v25, v28
	v_mul_f32_e32 v28, 0x3d922279, v26
	v_fmaak_f32 v28, v26, v28, 0x3fcc422a
	v_mul_f32_e32 v28, v26, v28
	v_mul_f32_e32 v28, 0xbfb8aa3b, v28
	v_exp_f32_e32 v28, v28
	v_add_co_u32_e32 v30, vcc, s2, v140
	s_mov_b32 s2, 0x58000
	v_add_f32_e32 v28, 1.0, v28
	v_rcp_f32_e32 v28, v28
	v_addc_co_u32_e32 v31, vcc, 0, v141, vcc
	v_mul_f32_e32 v26, v26, v28
	v_mul_f32_e32 v28, 0x3d922279, v27
	v_fmaak_f32 v28, v27, v28, 0x3fcc422a
	v_mul_f32_e32 v28, v27, v28
	v_mul_f32_e32 v28, 0xbfb8aa3b, v28
	v_exp_f32_e32 v28, v28
	s_nop 0
	v_add_f32_e32 v28, 1.0, v28
	v_rcp_f32_e32 v28, v28
	s_nop 0
	v_mul_f32_e32 v27, v27, v28
	v_cvt_pk_bf16_f32 v26, v26, v27
	v_mul_f32_e32 v27, 0x3d922279, v42
	v_fmaak_f32 v27, v42, v27, 0x3fcc422a
	v_mul_f32_e32 v28, 0x3d922279, v43
	v_mul_f32_e32 v27, v42, v27
	v_fmaak_f32 v28, v43, v28, 0x3fcc422a
	v_mul_f32_e32 v27, 0xbfb8aa3b, v27
	v_mul_f32_e32 v28, v43, v28
	v_exp_f32_e32 v27, v27
	v_mul_f32_e32 v28, 0xbfb8aa3b, v28
	v_exp_f32_e32 v28, v28
	v_add_f32_e32 v27, 1.0, v27
	v_rcp_f32_e32 v27, v27
	v_add_f32_e32 v28, 1.0, v28
	v_rcp_f32_e32 v28, v28
	v_mul_f32_e32 v27, v42, v27
	v_mul_f32_e32 v28, v43, v28
	v_cvt_pk_bf16_f32 v27, v27, v28
	global_store_dwordx4 v[30:31], v[24:27], off
	v_lshl_add_u64 v[28:29], v[140:141], 0, s[28:29]
	s_mov_b64 s[28:29], 0x58000
	v_pk_fma_f32 v[24:25], v[18:19], v[40:41], v[34:35] op_sel_hi:[1,0,1]
	v_pk_fma_f32 v[18:19], v[16:17], v[40:41], v[32:33] op_sel_hi:[1,0,1]
	v_mul_f32_e32 v16, 0x3d922279, v20
	v_mul_f32_e32 v17, 0x3d922279, v21
	v_fmaak_f32 v16, v20, v16, 0x3fcc422a
	v_fmaak_f32 v17, v21, v17, 0x3fcc422a
	v_mul_f32_e32 v16, v20, v16
	v_mul_f32_e32 v17, v21, v17
	v_mul_f32_e32 v16, 0xbfb8aa3b, v16
	v_mul_f32_e32 v17, 0xbfb8aa3b, v17
	v_exp_f32_e32 v16, v16
	v_exp_f32_e32 v17, v17
	v_add_f32_e32 v16, 1.0, v16
	v_add_f32_e32 v17, 1.0, v17
	v_rcp_f32_e32 v16, v16
	v_rcp_f32_e32 v17, v17
	v_mul_f32_e32 v16, v20, v16
	v_mul_f32_e32 v17, v21, v17
	v_cvt_pk_bf16_f32 v16, v16, v17
	v_mul_f32_e32 v17, 0x3d922279, v22
	v_mul_f32_e32 v20, 0x3d922279, v23
	v_fmaak_f32 v17, v22, v17, 0x3fcc422a
	v_fmaak_f32 v20, v23, v20, 0x3fcc422a
	v_mul_f32_e32 v17, v22, v17
	v_mul_f32_e32 v20, v23, v20
	v_mul_f32_e32 v17, 0xbfb8aa3b, v17
	v_mul_f32_e32 v20, 0xbfb8aa3b, v20
	v_exp_f32_e32 v17, v17
	v_exp_f32_e32 v20, v20
	v_add_f32_e32 v17, 1.0, v17
	v_add_f32_e32 v20, 1.0, v20
	v_rcp_f32_e32 v17, v17
	v_rcp_f32_e32 v20, v20
	v_mul_f32_e32 v17, v22, v17
	v_mul_f32_e32 v20, v23, v20
	v_cvt_pk_bf16_f32 v17, v17, v20
	v_mul_f32_e32 v20, 0x3d922279, v18
	v_fmaak_f32 v20, v18, v20, 0x3fcc422a
	v_mul_f32_e32 v20, v18, v20
	v_mul_f32_e32 v20, 0xbfb8aa3b, v20
	v_exp_f32_e32 v20, v20
	s_nop 0
	v_add_f32_e32 v20, 1.0, v20
	v_rcp_f32_e32 v20, v20
	s_nop 0
	v_mul_f32_e32 v18, v18, v20
	v_mul_f32_e32 v20, 0x3d922279, v19
	v_fmaak_f32 v20, v19, v20, 0x3fcc422a
	v_mul_f32_e32 v20, v19, v20
	v_mul_f32_e32 v20, 0xbfb8aa3b, v20
	v_exp_f32_e32 v20, v20
	s_nop 0
	v_add_f32_e32 v20, 1.0, v20
	v_rcp_f32_e32 v20, v20
	s_nop 0
	v_mul_f32_e32 v19, v19, v20
	v_cvt_pk_bf16_f32 v18, v18, v19
	v_mul_f32_e32 v19, 0x3d922279, v24
	v_fmaak_f32 v19, v24, v19, 0x3fcc422a
	v_mul_f32_e32 v20, 0x3d922279, v25
	v_mul_f32_e32 v19, v24, v19
	v_fmaak_f32 v20, v25, v20, 0x3fcc422a
	v_mul_f32_e32 v19, 0xbfb8aa3b, v19
	v_mul_f32_e32 v20, v25, v20
	v_exp_f32_e32 v19, v19
	v_mul_f32_e32 v20, 0xbfb8aa3b, v20
	v_exp_f32_e32 v20, v20
	v_add_f32_e32 v19, 1.0, v19
	v_rcp_f32_e32 v19, v19
	v_add_f32_e32 v20, 1.0, v20
	v_rcp_f32_e32 v20, v20
; __device__ __forceinline__ unsigned pk2(float lo, float hi) { unsigned r; asm volatile("v_cvt_pk_bf16_f32 %0, %1, %2" : "=v"(r) : "v"(lo), "v"(hi)); return r; }
; __device__ __forceinline__ float rstd_of(float ss) { return __builtin_amdgcn_rsqf(ss * (1.0f / 1024.0f) + EPS); }
; __device__ __forceinline__ float gelu_tanh_f(float v) {
;     const float z2 = v * (1.5957691216057308f + 0.07135481627159493f * v * v);
;     return v * __builtin_amdgcn_rcpf(1.0f + __builtin_amdgcn_exp2f(-1.4426950408889634f * z2));
; }
;     __device__ __forceinline__ void operator()(const f32x4 (&acc)[2][2][4][2], const Unit& u, int wr, int wc, int fr_, int fq_) const {
;     ...
;         for (int ai = 0; ai < 2; ++ai)
; #pragma unroll
;             for (int m = 0; m < 4; ++m) {
;                 const int r = row0 + ai * 128 + m * 16; const float rs = rstd_of(rowss[r]);
; #pragma unroll
;                 for (int bj = 0; bj < 2; ++bj) {
;                     const f32x4 v0 = acc[ai][bj][m][0] * rs + bv[bj][0], v1 = acc[ai][bj][m][1] * rs + bv[bj][1];
;                     u32x4 w; w.x = pk2(gelu_tanh_f(v0[0]), gelu_tanh_f(v0[1])); w.y = pk2(gelu_tanh_f(v0[2]), gelu_tanh_f(v0[3]));
;                     w.z = pk2(gelu_tanh_f(v1[0]), gelu_tanh_f(v1[1])); w.w = pk2(gelu_tanh_f(v1[2]), gelu_tanh_f(v1[3]));
;                     *(u32x4*)(O + (size_t)r * 1024 + col0 + bj * 128) = w;
	v_mul_f32_e32 v19, v24, v19
	v_mul_f32_e32 v20, v25, v20
	v_cvt_pk_bf16_f32 v19, v19, v20
	global_store_dwordx4 v[28:29], v[16:19], off offset:256
	s_nop 1
	v_mov_b32_e32 v16, v184
	v_fmamk_f32 v16, v16, 0x3a800000, v213
	v_rsq_f32_e32 v16, v16
	s_nop 0
	v_pk_fma_f32 v[12:13], v[12:13], v[16:17], v[52:53] op_sel_hi:[1,0,1]
	v_pk_fma_f32 v[18:19], v[10:11], v[16:17], v[50:51] op_sel_hi:[1,0,1]
	v_pk_fma_f32 v[10:11], v[8:9], v[16:17], v[48:49] op_sel_hi:[1,0,1]
	v_mul_f32_e32 v8, 0x3d922279, v12
	v_mul_f32_e32 v9, 0x3d922279, v13
	v_fmaak_f32 v8, v12, v8, 0x3fcc422a
	v_fmaak_f32 v9, v13, v9, 0x3fcc422a
	v_mul_f32_e32 v8, v12, v8
	v_mul_f32_e32 v9, v13, v9
	v_mul_f32_e32 v8, 0xbfb8aa3b, v8
	v_mul_f32_e32 v9, 0xbfb8aa3b, v9
	v_exp_f32_e32 v8, v8
	v_exp_f32_e32 v9, v9
	v_pk_fma_f32 v[14:15], v[14:15], v[16:17], v[54:55] op_sel_hi:[1,0,1]
	v_pk_fma_f32 v[4:5], v[4:5], v[16:17], v[36:37] op_sel_hi:[1,0,1]
	v_add_f32_e32 v8, 1.0, v8
	v_add_f32_e32 v9, 1.0, v9
	v_rcp_f32_e32 v8, v8
	v_rcp_f32_e32 v9, v9
	v_pk_fma_f32 v[6:7], v[6:7], v[16:17], v[38:39] op_sel_hi:[1,0,1]
	v_mul_f32_e32 v8, v12, v8
	v_mul_f32_e32 v9, v13, v9
	v_cvt_pk_bf16_f32 v8, v8, v9
	v_mul_f32_e32 v9, 0x3d922279, v14
	v_mul_f32_e32 v12, 0x3d922279, v15
	v_fmaak_f32 v9, v14, v9, 0x3fcc422a
	v_fmaak_f32 v12, v15, v12, 0x3fcc422a
	v_mul_f32_e32 v9, v14, v9
	v_mul_f32_e32 v12, v15, v12
	v_mul_f32_e32 v9, 0xbfb8aa3b, v9
	v_mul_f32_e32 v12, 0xbfb8aa3b, v12
	v_exp_f32_e32 v9, v9
	v_exp_f32_e32 v12, v12
	v_add_f32_e32 v9, 1.0, v9
	v_add_f32_e32 v12, 1.0, v12
	v_rcp_f32_e32 v9, v9
	v_rcp_f32_e32 v12, v12
	v_mul_f32_e32 v9, v14, v9
	v_mul_f32_e32 v12, v15, v12
	v_cvt_pk_bf16_f32 v9, v9, v12
	v_mul_f32_e32 v12, 0x3d922279, v10
	v_fmaak_f32 v12, v10, v12, 0x3fcc422a
	v_mul_f32_e32 v12, v10, v12
	v_mul_f32_e32 v12, 0xbfb8aa3b, v12
	v_exp_f32_e32 v12, v12
	v_add_co_u32_e32 v14, vcc, s2, v140
	v_add_f32_e32 v12, 1.0, v12
	v_rcp_f32_e32 v12, v12
	v_addc_co_u32_e32 v15, vcc, 0, v141, vcc
	s_andn2_b64 vcc, exec, s[38:39]
	v_mul_f32_e32 v10, v10, v12
	v_mul_f32_e32 v12, 0x3d922279, v11
	v_fmaak_f32 v12, v11, v12, 0x3fcc422a
	v_mul_f32_e32 v12, v11, v12
	v_mul_f32_e32 v12, 0xbfb8aa3b, v12
	v_exp_f32_e32 v12, v12
	s_nop 0
	v_add_f32_e32 v12, 1.0, v12
	v_rcp_f32_e32 v12, v12
	s_nop 0
	v_mul_f32_e32 v11, v11, v12
	v_cvt_pk_bf16_f32 v10, v10, v11
	v_mul_f32_e32 v11, 0x3d922279, v18
	v_fmaak_f32 v11, v18, v11, 0x3fcc422a
	v_mul_f32_e32 v12, 0x3d922279, v19
	v_mul_f32_e32 v11, v18, v11
	v_fmaak_f32 v12, v19, v12, 0x3fcc422a
	v_mul_f32_e32 v11, 0xbfb8aa3b, v11
	v_mul_f32_e32 v12, v19, v12
	v_exp_f32_e32 v11, v11
	v_mul_f32_e32 v12, 0xbfb8aa3b, v12
	v_exp_f32_e32 v12, v12
	v_add_f32_e32 v11, 1.0, v11
	v_rcp_f32_e32 v11, v11
	v_add_f32_e32 v12, 1.0, v12
	v_rcp_f32_e32 v12, v12
	v_mul_f32_e32 v11, v18, v11
	v_mul_f32_e32 v12, v19, v12
	v_cvt_pk_bf16_f32 v11, v11, v12
	global_store_dwordx4 v[14:15], v[8:11], off
	v_lshl_add_u64 v[12:13], v[140:141], 0, s[28:29]
	s_nop 0
	v_pk_fma_f32 v[8:9], v[2:3], v[16:17], v[34:35] op_sel_hi:[1,0,1]
	v_pk_fma_f32 v[2:3], v[0:1], v[16:17], v[32:33] op_sel_hi:[1,0,1]
	v_mul_f32_e32 v0, 0x3d922279, v4
	v_mul_f32_e32 v1, 0x3d922279, v5
	v_fmaak_f32 v0, v4, v0, 0x3fcc422a
	v_fmaak_f32 v1, v5, v1, 0x3fcc422a
	v_mul_f32_e32 v0, v4, v0
	v_mul_f32_e32 v1, v5, v1
	v_mul_f32_e32 v0, 0xbfb8aa3b, v0
	v_mul_f32_e32 v1, 0xbfb8aa3b, v1
	v_exp_f32_e32 v0, v0
	v_exp_f32_e32 v1, v1
	v_add_f32_e32 v0, 1.0, v0
	v_add_f32_e32 v1, 1.0, v1
	v_rcp_f32_e32 v0, v0
	v_rcp_f32_e32 v1, v1
	v_mul_f32_e32 v0, v4, v0
	v_mul_f32_e32 v1, v5, v1
	v_cvt_pk_bf16_f32 v0, v0, v1
	v_mul_f32_e32 v1, 0x3d922279, v6
	v_mul_f32_e32 v4, 0x3d922279, v7
	v_fmaak_f32 v1, v6, v1, 0x3fcc422a
	v_fmaak_f32 v4, v7, v4, 0x3fcc422a
	v_mul_f32_e32 v1, v6, v1
	v_mul_f32_e32 v4, v7, v4
	v_mul_f32_e32 v1, 0xbfb8aa3b, v1
	v_mul_f32_e32 v4, 0xbfb8aa3b, v4
	v_exp_f32_e32 v1, v1
	v_exp_f32_e32 v4, v4
	v_add_f32_e32 v1, 1.0, v1
	v_add_f32_e32 v4, 1.0, v4
	v_rcp_f32_e32 v1, v1
	v_rcp_f32_e32 v4, v4
	v_mul_f32_e32 v1, v6, v1
	v_mul_f32_e32 v4, v7, v4
	v_cvt_pk_bf16_f32 v1, v1, v4
	v_mul_f32_e32 v4, 0x3d922279, v2
	v_fmaak_f32 v4, v2, v4, 0x3fcc422a
	v_mul_f32_e32 v4, v2, v4
	v_mul_f32_e32 v4, 0xbfb8aa3b, v4
	v_exp_f32_e32 v4, v4
	s_nop 0
	v_add_f32_e32 v4, 1.0, v4
	v_rcp_f32_e32 v4, v4
	s_nop 0
	v_mul_f32_e32 v2, v2, v4
	v_mul_f32_e32 v4, 0x3d922279, v3
	v_fmaak_f32 v4, v3, v4, 0x3fcc422a
	v_mul_f32_e32 v4, v3, v4
	v_mul_f32_e32 v4, 0xbfb8aa3b, v4
	v_exp_f32_e32 v4, v4
	s_nop 0
	v_add_f32_e32 v4, 1.0, v4
	v_rcp_f32_e32 v4, v4
	s_nop 0
	v_mul_f32_e32 v3, v3, v4
	v_cvt_pk_bf16_f32 v2, v2, v3
	v_mul_f32_e32 v3, 0x3d922279, v8
	v_fmaak_f32 v3, v8, v3, 0x3fcc422a
	v_mul_f32_e32 v4, 0x3d922279, v9
	v_mul_f32_e32 v3, v8, v3
	v_fmaak_f32 v4, v9, v4, 0x3fcc422a
	v_mul_f32_e32 v3, 0xbfb8aa3b, v3
	v_mul_f32_e32 v4, v9, v4
	v_exp_f32_e32 v3, v3
	v_mul_f32_e32 v4, 0xbfb8aa3b, v4
	v_exp_f32_e32 v4, v4
	v_add_f32_e32 v3, 1.0, v3
	v_rcp_f32_e32 v3, v3
	v_add_f32_e32 v4, 1.0, v4
	v_rcp_f32_e32 v4, v4
	v_mul_f32_e32 v3, v8, v3
	v_mul_f32_e32 v4, v9, v4
	v_cvt_pk_bf16_f32 v3, v3, v4
	global_store_dwordx4 v[12:13], v[0:3], off offset:256
	s_cbranch_vccnz .LBB0_459
	s_andn2_b64 vcc, exec, s[0:1]
	s_cbranch_vccnz .LBB0_458
	s_barrier
	s_branch .LBB0_458

; __device__ __forceinline__ unsigned pk2(float lo, float hi) { unsigned r; asm volatile("v_cvt_pk_bf16_f32 %0, %1, %2" : "=v"(r) : "v"(lo), "v"(hi)); return r; }
; __device__ __forceinline__ float rstd_of(float ss) { return __builtin_amdgcn_rsqf(ss * (1.0f / 1024.0f) + EPS); }
;     __device__ __forceinline__ void operator()(const f32x4 (&acc)[2][2][4][2], const Unit& u, int wr, int wc, int fr_, int fq_) const {
;     ...
;         const int mb = mb_of_panel(u.pn), tok0 = u.pn * 256 + wc * 32 + 8 * fq;
;         f32x4 rs[2][2];
; #pragma unroll
;         for (int bj = 0; bj < 2; ++bj)
; #pragma unroll
;             for (int n = 0; n < 2; ++n) { const f32x4 s = *(const f32x4*)(rowss + tok0 + bj * 128 + 4 * n);
;                 rs[bj][n] = (f32x4){rstd_of(s[0]), rstd_of(s[1]), rstd_of(s[2]), rstd_of(s[3])}; }
; #pragma unroll
;         for (int ai = 0; ai < 2; ++ai)
; #pragma unroll
;             for (int m = 0; m < 4; ++m) {
;                 const int ch = u.pm * 256 + ai * 128 + wr * 64 + m * 16 + fr, part = ch >> 9, c = ch & 511;
;                 const float swv = sw[(size_t)mb * NGU + ch];
; #pragma unroll
;                 for (int bj = 0; bj < 2; ++bj) {
;                     const f32x4 v0 = acc[ai][bj][m][0] * rs[bj][0] + swv, v1 = acc[ai][bj][m][1] * rs[bj][1] + swv;
;                     u32x4 w; w.x = pk2(v0[0], v0[1]); w.y = pk2(v0[2], v0[3]); w.z = pk2(v1[0], v1[1]); w.w = pk2(v1[2], v1[3]);
;                     bf16_t* dst;
;                     if (u.pn < 128) { const int b = u.pn >> 4, npos = (u.pn & 15) * 256 + bj * 128 + wc * 32 + 8 * fq; dst = FT + ((size_t)(b * 512 + c) * 8192 + part * 4096 + npos); }
;                     else { const int b = u.pn - 128, npos = bj * 128 + wc * 32 + 8 * fq; dst = FTC + ((size_t)(b * 512 + c) * 512 + part * 256 + npos); }
;                     *(u32x4*)dst = w;
.LBB0_484:
	v_mov_b32_e32 v160, v211
	s_lshl_b32 s28, s42, 8
	v_lshrrev_b32_e32 v128, 1, v160
	v_and_b32_e32 v161, 24, v128
	v_or_b32_e32 v148, s58, v161
	v_or_b32_e32 v128, s28, v148
	v_ashrrev_i32_e32 v129, 31, v128
	v_lshl_add_u64 v[150:151], v[128:129], 2, s[62:63]
	global_load_dwordx4 v[128:131], v[150:151], off offset:16
	global_load_dwordx4 v[132:135], v[150:151], off
	s_min_i32 s3, s42, 0x80
	s_lshl_b32 s45, s40, 8
	s_ashr_i32 s3, s3, 4
	s_add_i32 s45, s45, s57
	s_cmpk_lt_i32 s42, 0x80
	s_cselect_b64 s[40:41], -1, 0
	s_cmpk_gt_i32 s42, 0x7f
	s_cselect_b64 s[86:87], -1, 0
	s_ashr_i32 s43, s45, 9
	s_lshl_b32 s67, s42, 9
	s_and_b32 s28, s28, 0xf00
	s_lshl_b32 s82, s43, 8
	s_mul_hi_i32 s29, s3, 0x5800
	s_mulk_i32 s3, 0x5800
	s_add_i32 s67, s67, 0xffff0000
	s_or_b32 s28, s58, s28
	s_ashr_i32 s83, s82, 31
	s_movk_i32 s4, 0x1cf
	s_add_u32 s80, s51, s3
	s_addc_u32 s81, s54, s29
	s_mov_b64 s[46:47], -1
	s_and_b64 vcc, exec, s[86:87]
	s_waitcnt vmcnt(0)
	v_fmamk_f32 v128, v128, 0x3a800000, v213
	v_fmamk_f32 v132, v132, 0x3a800000, v213
	v_rsq_f32_e32 v152, v132
	v_fmamk_f32 v132, v133, 0x3a800000, v213
	v_rsq_f32_e32 v156, v128
	v_fmamk_f32 v128, v129, 0x3a800000, v213
	v_rsq_f32_e32 v153, v132
	v_fmamk_f32 v132, v134, 0x3a800000, v213
	v_rsq_f32_e32 v157, v128
	v_fmamk_f32 v128, v130, 0x3a800000, v213
	v_rsq_f32_e32 v154, v132
	v_fmamk_f32 v132, v135, 0x3a800000, v213
	v_rsq_f32_e32 v158, v128
	v_fmamk_f32 v128, v131, 0x3a800000, v213
	v_rsq_f32_e32 v155, v132
	v_rsq_f32_e32 v159, v128
	global_load_dwordx4 v[128:131], v[150:151], off offset:528
	global_load_dwordx4 v[132:135], v[150:151], off offset:512
	v_and_b32_e32 v151, 15, v160
	v_or_b32_e32 v150, s28, v161
	v_or_b32_e32 v160, s45, v151
	v_mov_b32_e32 v161, s45
	v_bitop3_b32 v165, v151, s4, v161 bitop3:0xc8
	v_ashrrev_i32_e32 v161, 31, v160
	v_lshl_add_u64 v[162:163], v[160:161], 2, s[80:81]
	global_load_dword v164, v[162:163], off
	global_load_dword v176, v[162:163], off offset:64
	global_load_dword v177, v[162:163], off offset:128
	global_load_dword v178, v[162:163], off offset:192
	global_load_dword v179, v[162:163], off offset:512
	global_load_dword v180, v[162:163], off offset:576
	global_load_dword v181, v[162:163], off offset:640
	global_load_dword v182, v[162:163], off offset:704
	v_or_b32_e32 v208, s67, v165
	v_readlane_b32 s28, v252, 33
	v_lshlrev_b64 v[166:167], 10, v[208:209]
	v_readlane_b32 s29, v252, 34
	s_waitcnt vmcnt(0)
	v_pk_fma_f32 v[126:127], v[126:127], v[154:155], v[164:165] op_sel_hi:[1,1,0]
	v_pk_fma_f32 v[124:125], v[124:125], v[152:153], v[164:165] op_sel_hi:[1,1,0]
	v_pk_fma_f32 v[168:169], v[122:123], v[158:159], v[164:165] op_sel_hi:[1,1,0]
	v_pk_fma_f32 v[122:123], v[120:121], v[156:157], v[164:165] op_sel_hi:[1,1,0]
	v_cvt_pk_bf16_f32 v120, v124, v125
	v_cvt_pk_bf16_f32 v121, v126, v127
	v_lshl_add_u64 v[126:127], s[28:29], 0, v[166:167]
	v_cvt_pk_bf16_f32 v122, v122, v123
	v_cvt_pk_bf16_f32 v123, v168, v169
	v_lshlrev_b32_e32 v124, 1, v148
	v_lshl_add_u64 v[166:167], s[82:83], 1, v[126:127]
	v_mov_b64_e32 v[168:169], v[150:151]
	s_cbranch_vccz .LBB0_486
	v_mov_b32_e32 v125, v209
	v_lshl_add_u64 v[170:171], v[166:167], 0, v[124:125]
	s_mov_b64 s[46:47], 0
	v_mov_b64_e32 v[168:169], v[148:149]

; __device__ __forceinline__ unsigned pk2(float lo, float hi) { unsigned r; asm volatile("v_cvt_pk_bf16_f32 %0, %1, %2" : "=v"(r) : "v"(lo), "v"(hi)); return r; }
;     __device__ __forceinline__ void operator()(const f32x4 (&acc)[2][2][4][2], const Unit& u, int wr, int wc, int fr_, int fq_) const {
;     ...
;             for (int m = 0; m < 4; ++m) {
;                 const int ch = u.pm * 256 + ai * 128 + wr * 64 + m * 16 + fr, part = ch >> 9, c = ch & 511;
;                 const float swv = sw[(size_t)mb * NGU + ch];
; #pragma unroll
;                 for (int bj = 0; bj < 2; ++bj) {
;                     const f32x4 v0 = acc[ai][bj][m][0] * rs[bj][0] + swv, v1 = acc[ai][bj][m][1] * rs[bj][1] + swv;
;                     u32x4 w; w.x = pk2(v0[0], v0[1]); w.y = pk2(v0[2], v0[3]); w.z = pk2(v1[0], v1[1]); w.w = pk2(v1[2], v1[3]);
;                     bf16_t* dst;
;                     if (u.pn < 128) { const int b = u.pn >> 4, npos = (u.pn & 15) * 256 + bj * 128 + wc * 32 + 8 * fq; dst = FT + ((size_t)(b * 512 + c) * 8192 + part * 4096 + npos); }
;                     else { const int b = u.pn - 128, npos = bj * 128 + wc * 32 + 8 * fq; dst = FTC + ((size_t)(b * 512 + c) * 512 + part * 256 + npos); }
;                     *(u32x4*)dst = w;
.LBB0_488:
	v_fmamk_f32 v125, v132, 0x3a800000, v213
	v_rsq_f32_e32 v132, v125
	v_fmamk_f32 v125, v133, 0x3a800000, v213
	v_rsq_f32_e32 v133, v125
	v_fmamk_f32 v125, v134, 0x3a800000, v213
	v_rsq_f32_e32 v134, v125
	v_fmamk_f32 v125, v135, 0x3a800000, v213
	v_rsq_f32_e32 v135, v125
	v_fmamk_f32 v125, v128, 0x3a800000, v213
	v_rsq_f32_e32 v128, v125
	v_fmamk_f32 v125, v129, 0x3a800000, v213
	v_rsq_f32_e32 v129, v125
	v_fmamk_f32 v125, v130, 0x3a800000, v213
	v_rsq_f32_e32 v130, v125
	v_fmamk_f32 v125, v131, 0x3a800000, v213
	v_rsq_f32_e32 v131, v125
	v_mov_b32_e32 v165, v164
	global_store_dwordx4 v[170:171], v[120:123], off
	v_pk_fma_f32 v[116:117], v[116:117], v[132:133], v[164:165]
	v_lshlrev_b32_e32 v208, 1, v168
	v_mov_b32_e32 v120, v164
	v_mov_b32_e32 v121, v164
	v_pk_fma_f32 v[118:119], v[118:119], v[134:135], v[120:121]
	v_pk_fma_f32 v[120:121], v[114:115], v[130:131], v[120:121]
	v_pk_fma_f32 v[114:115], v[112:113], v[128:129], v[164:165]
	v_cvt_pk_bf16_f32 v112, v116, v117
	v_cndmask_b32_e64 v117, v167, v173, s[40:41]
	v_cndmask_b32_e64 v116, v166, v172, s[40:41]
	v_lshl_add_u64 v[116:117], v[116:117], 0, v[208:209]
	v_cvt_pk_bf16_f32 v113, v118, v119
	v_cvt_pk_bf16_f32 v114, v114, v115
	v_cvt_pk_bf16_f32 v115, v120, v121
	global_store_dwordx4 v[116:117], v[112:115], off offset:256
	s_nop 1
	v_mov_b32_e32 v112, v176
	s_movk_i32 s3, 0x1df
	v_bitop3_b32 v113, v160, s3, 16 bitop3:0xc8
	v_cndmask_b32_e64 v114, 0, 1, s[86:87]
	v_or_b32_e32 v208, s67, v113
	s_andn2_b64 vcc, exec, s[86:87]
	v_readlane_b32 s86, v252, 33
	v_cmp_ne_u32_e64 s[42:43], 1, v114
	v_lshlrev_b64 v[114:115], 10, v[208:209]
	v_readlane_b32 s87, v252, 34
	s_mov_b64 s[46:47], -1
	v_pk_fma_f32 v[108:109], v[108:109], v[152:153], v[112:113] op_sel_hi:[1,1,0]
	v_lshl_add_u64 v[114:115], s[86:87], 0, v[114:115]
	v_lshl_add_u64 v[114:115], s[82:83], 1, v[114:115]
	v_pk_fma_f32 v[118:119], v[106:107], v[158:159], v[112:113] op_sel_hi:[1,1,0]
	v_pk_fma_f32 v[106:107], v[104:105], v[156:157], v[112:113] op_sel_hi:[1,1,0]
	v_cvt_pk_bf16_f32 v104, v108, v109
	v_mov_b64_e32 v[108:109], v[150:151]
	v_pk_fma_f32 v[110:111], v[110:111], v[154:155], v[112:113] op_sel_hi:[1,1,0]
	s_nop 0
	v_cvt_pk_bf16_f32 v105, v110, v111
	v_cvt_pk_bf16_f32 v106, v106, v107
	v_cvt_pk_bf16_f32 v107, v118, v119
	s_cbranch_vccnz .LBB0_490
	v_mov_b32_e32 v125, v209
	v_lshl_add_u64 v[116:117], v[114:115], 0, v[124:125]
	s_mov_b64 s[46:47], 0
	v_mov_b64_e32 v[108:109], v[148:149]

; __device__ __forceinline__ unsigned pk2(float lo, float hi) { unsigned r; asm volatile("v_cvt_pk_bf16_f32 %0, %1, %2" : "=v"(r) : "v"(lo), "v"(hi)); return r; }
;     __device__ __forceinline__ void operator()(const f32x4 (&acc)[2][2][4][2], const Unit& u, int wr, int wc, int fr_, int fq_) const {
;     ...
;             for (int m = 0; m < 4; ++m) {
;                 const int ch = u.pm * 256 + ai * 128 + wr * 64 + m * 16 + fr, part = ch >> 9, c = ch & 511;
;                 const float swv = sw[(size_t)mb * NGU + ch];
; #pragma unroll
;                 for (int bj = 0; bj < 2; ++bj) {
;                     const f32x4 v0 = acc[ai][bj][m][0] * rs[bj][0] + swv, v1 = acc[ai][bj][m][1] * rs[bj][1] + swv;
;                     u32x4 w; w.x = pk2(v0[0], v0[1]); w.y = pk2(v0[2], v0[3]); w.z = pk2(v1[0], v1[1]); w.w = pk2(v1[2], v1[3]);
;                     bf16_t* dst;
;                     if (u.pn < 128) { const int b = u.pn >> 4, npos = (u.pn & 15) * 256 + bj * 128 + wc * 32 + 8 * fq; dst = FT + ((size_t)(b * 512 + c) * 8192 + part * 4096 + npos); }
;                     else { const int b = u.pn - 128, npos = bj * 128 + wc * 32 + 8 * fq; dst = FTC + ((size_t)(b * 512 + c) * 512 + part * 256 + npos); }
;                     *(u32x4*)dst = w;
.LBB0_492:
	v_mov_b32_e32 v113, v112
	global_store_dwordx4 v[116:117], v[104:107], off
	v_pk_fma_f32 v[100:101], v[100:101], v[132:133], v[112:113]
	v_lshlrev_b32_e32 v208, 1, v108
	v_mov_b32_e32 v104, v112
	v_mov_b32_e32 v105, v112
	v_pk_fma_f32 v[102:103], v[102:103], v[134:135], v[104:105]
	v_pk_fma_f32 v[104:105], v[98:99], v[130:131], v[104:105]
	v_pk_fma_f32 v[98:99], v[96:97], v[128:129], v[112:113]
	v_cvt_pk_bf16_f32 v96, v100, v101
	v_cndmask_b32_e64 v101, v115, v111, s[40:41]
	v_cndmask_b32_e64 v100, v114, v110, s[40:41]
	v_lshl_add_u64 v[100:101], v[100:101], 0, v[208:209]
	v_cvt_pk_bf16_f32 v97, v102, v103
	v_cvt_pk_bf16_f32 v98, v98, v99
	v_cvt_pk_bf16_f32 v99, v104, v105
	global_store_dwordx4 v[100:101], v[96:99], off offset:256
	s_nop 1
	v_mov_b32_e32 v96, v177
	s_movk_i32 s3, 0x1ef
	v_bitop3_b32 v97, v160, s3, 32 bitop3:0xc8
	v_or_b32_e32 v208, s67, v97
	v_readlane_b32 s86, v252, 33
	v_lshlrev_b64 v[98:99], 10, v[208:209]
	v_readlane_b32 s87, v252, 34
	s_mov_b64 s[46:47], -1
	s_and_b64 vcc, exec, s[42:43]
	v_lshl_add_u64 v[98:99], s[86:87], 0, v[98:99]
	v_lshl_add_u64 v[98:99], s[82:83], 1, v[98:99]
	v_pk_fma_f32 v[92:93], v[92:93], v[152:153], v[96:97] op_sel_hi:[1,1,0]
	v_pk_fma_f32 v[102:103], v[90:91], v[158:159], v[96:97] op_sel_hi:[1,1,0]
	v_pk_fma_f32 v[90:91], v[88:89], v[156:157], v[96:97] op_sel_hi:[1,1,0]
	v_cvt_pk_bf16_f32 v88, v92, v93
	v_mov_b64_e32 v[92:93], v[150:151]
	v_pk_fma_f32 v[94:95], v[94:95], v[154:155], v[96:97] op_sel_hi:[1,1,0]
	s_nop 0
	v_cvt_pk_bf16_f32 v89, v94, v95
	v_cvt_pk_bf16_f32 v90, v90, v91
	v_cvt_pk_bf16_f32 v91, v102, v103
	s_cbranch_vccnz .LBB0_494
	v_mov_b32_e32 v125, v209
	v_lshl_add_u64 v[100:101], v[98:99], 0, v[124:125]
	s_mov_b64 s[46:47], 0
	v_mov_b64_e32 v[92:93], v[148:149]

; __device__ __forceinline__ unsigned pk2(float lo, float hi) { unsigned r; asm volatile("v_cvt_pk_bf16_f32 %0, %1, %2" : "=v"(r) : "v"(lo), "v"(hi)); return r; }
;     __device__ __forceinline__ void operator()(const f32x4 (&acc)[2][2][4][2], const Unit& u, int wr, int wc, int fr_, int fq_) const {
;     ...
;             for (int m = 0; m < 4; ++m) {
;                 const int ch = u.pm * 256 + ai * 128 + wr * 64 + m * 16 + fr, part = ch >> 9, c = ch & 511;
;                 const float swv = sw[(size_t)mb * NGU + ch];
; #pragma unroll
;                 for (int bj = 0; bj < 2; ++bj) {
;                     const f32x4 v0 = acc[ai][bj][m][0] * rs[bj][0] + swv, v1 = acc[ai][bj][m][1] * rs[bj][1] + swv;
;                     u32x4 w; w.x = pk2(v0[0], v0[1]); w.y = pk2(v0[2], v0[3]); w.z = pk2(v1[0], v1[1]); w.w = pk2(v1[2], v1[3]);
;                     bf16_t* dst;
;                     if (u.pn < 128) { const int b = u.pn >> 4, npos = (u.pn & 15) * 256 + bj * 128 + wc * 32 + 8 * fq; dst = FT + ((size_t)(b * 512 + c) * 8192 + part * 4096 + npos); }
;                     else { const int b = u.pn - 128, npos = bj * 128 + wc * 32 + 8 * fq; dst = FTC + ((size_t)(b * 512 + c) * 512 + part * 256 + npos); }
;                     *(u32x4*)dst = w;
.LBB0_496:
	v_mov_b32_e32 v97, v96
	global_store_dwordx4 v[100:101], v[88:91], off
	v_pk_fma_f32 v[84:85], v[84:85], v[132:133], v[96:97]
	v_lshlrev_b32_e32 v208, 1, v92
	v_mov_b32_e32 v88, v96
	v_mov_b32_e32 v89, v96
	v_pk_fma_f32 v[86:87], v[86:87], v[134:135], v[88:89]
	v_pk_fma_f32 v[88:89], v[82:83], v[130:131], v[88:89]
	v_pk_fma_f32 v[82:83], v[80:81], v[128:129], v[96:97]
	v_cvt_pk_bf16_f32 v80, v84, v85
	v_cndmask_b32_e64 v85, v99, v95, s[40:41]
	v_cndmask_b32_e64 v84, v98, v94, s[40:41]
	v_lshl_add_u64 v[84:85], v[84:85], 0, v[208:209]
	v_cvt_pk_bf16_f32 v81, v86, v87
	v_cvt_pk_bf16_f32 v82, v82, v83
	v_cvt_pk_bf16_f32 v83, v88, v89
	global_store_dwordx4 v[84:85], v[80:83], off offset:256
	s_nop 1
	v_mov_b32_e32 v80, v178
	v_readlane_b32 s86, v252, 33
	v_bitop3_b32 v81, v160, s6, 48 bitop3:0xc8
	v_or_b32_e32 v208, s67, v81
	v_lshlrev_b64 v[82:83], 10, v[208:209]
	v_readlane_b32 s87, v252, 34
	s_mov_b64 s[46:47], -1
	s_and_b64 vcc, exec, s[42:43]
	v_lshl_add_u64 v[82:83], s[86:87], 0, v[82:83]
	v_lshl_add_u64 v[82:83], s[82:83], 1, v[82:83]
	v_pk_fma_f32 v[76:77], v[76:77], v[152:153], v[80:81] op_sel_hi:[1,1,0]
	v_pk_fma_f32 v[86:87], v[74:75], v[158:159], v[80:81] op_sel_hi:[1,1,0]
	v_pk_fma_f32 v[74:75], v[72:73], v[156:157], v[80:81] op_sel_hi:[1,1,0]
	v_cvt_pk_bf16_f32 v72, v76, v77
	v_mov_b64_e32 v[76:77], v[150:151]
	v_pk_fma_f32 v[78:79], v[78:79], v[154:155], v[80:81] op_sel_hi:[1,1,0]
	s_nop 0
	v_cvt_pk_bf16_f32 v73, v78, v79
	v_cvt_pk_bf16_f32 v74, v74, v75
	v_cvt_pk_bf16_f32 v75, v86, v87
	s_cbranch_vccnz .LBB0_498
	v_mov_b32_e32 v125, v209
	v_lshl_add_u64 v[84:85], v[82:83], 0, v[124:125]
	s_mov_b64 s[46:47], 0
	v_mov_b64_e32 v[76:77], v[148:149]

; __device__ __forceinline__ unsigned pk2(float lo, float hi) { unsigned r; asm volatile("v_cvt_pk_bf16_f32 %0, %1, %2" : "=v"(r) : "v"(lo), "v"(hi)); return r; }
;     __device__ __forceinline__ void operator()(const f32x4 (&acc)[2][2][4][2], const Unit& u, int wr, int wc, int fr_, int fq_) const {
;     ...
;             for (int m = 0; m < 4; ++m) {
;                 const int ch = u.pm * 256 + ai * 128 + wr * 64 + m * 16 + fr, part = ch >> 9, c = ch & 511;
;                 const float swv = sw[(size_t)mb * NGU + ch];
; #pragma unroll
;                 for (int bj = 0; bj < 2; ++bj) {
;                     const f32x4 v0 = acc[ai][bj][m][0] * rs[bj][0] + swv, v1 = acc[ai][bj][m][1] * rs[bj][1] + swv;
;                     u32x4 w; w.x = pk2(v0[0], v0[1]); w.y = pk2(v0[2], v0[3]); w.z = pk2(v1[0], v1[1]); w.w = pk2(v1[2], v1[3]);
;                     bf16_t* dst;
;                     if (u.pn < 128) { const int b = u.pn >> 4, npos = (u.pn & 15) * 256 + bj * 128 + wc * 32 + 8 * fq; dst = FT + ((size_t)(b * 512 + c) * 8192 + part * 4096 + npos); }
;                     else { const int b = u.pn - 128, npos = bj * 128 + wc * 32 + 8 * fq; dst = FTC + ((size_t)(b * 512 + c) * 512 + part * 256 + npos); }
;                     *(u32x4*)dst = w;
.LBB0_500:
	v_mov_b32_e32 v81, v80
	global_store_dwordx4 v[84:85], v[72:75], off
	v_pk_fma_f32 v[68:69], v[68:69], v[132:133], v[80:81]
	v_lshlrev_b32_e32 v208, 1, v76
	v_mov_b32_e32 v72, v80
	v_mov_b32_e32 v73, v80
	v_pk_fma_f32 v[70:71], v[70:71], v[134:135], v[72:73]
	v_pk_fma_f32 v[72:73], v[66:67], v[130:131], v[72:73]
	v_pk_fma_f32 v[66:67], v[64:65], v[128:129], v[80:81]
	v_cvt_pk_bf16_f32 v64, v68, v69
	v_cndmask_b32_e64 v69, v83, v79, s[40:41]
	v_cndmask_b32_e64 v68, v82, v78, s[40:41]
	v_lshl_add_u64 v[68:69], v[68:69], 0, v[208:209]
	s_add_i32 s3, s45, 0x80
	v_cvt_pk_bf16_f32 v65, v70, v71
	v_cvt_pk_bf16_f32 v66, v66, v67
	v_cvt_pk_bf16_f32 v67, v72, v73
	global_store_dwordx4 v[68:69], v[64:67], off offset:256
	s_ashr_i32 s44, s3, 9
	v_readlane_b32 s82, v252, 33
	v_or_b32_e32 v64, s3, v151
	v_ashrrev_i32_e32 v65, 31, v64
	v_lshl_add_u64 v[66:67], v[64:65], 2, s[80:81]
	s_nop 1
	v_mov_b32_e32 v68, v179
	v_mov_b32_e32 v65, s3
	s_movk_i32 s3, 0x1cf
	v_bitop3_b32 v65, v151, s3, v65 bitop3:0xc8
	v_or_b32_e32 v208, s67, v65
	s_lshl_b32 s80, s44, 8
	v_lshlrev_b64 v[70:71], 10, v[208:209]
	v_readlane_b32 s83, v252, 34
	s_ashr_i32 s81, s80, 31
	s_mov_b64 s[46:47], -1
	v_lshl_add_u64 v[70:71], s[82:83], 0, v[70:71]
	s_and_b64 vcc, exec, s[42:43]
	v_lshl_add_u64 v[70:71], s[80:81], 1, v[70:71]
	v_pk_fma_f32 v[60:61], v[60:61], v[152:153], v[68:69] op_sel_hi:[1,1,0]
	v_pk_fma_f32 v[74:75], v[58:59], v[158:159], v[68:69] op_sel_hi:[1,1,0]
	v_pk_fma_f32 v[58:59], v[56:57], v[156:157], v[68:69] op_sel_hi:[1,1,0]
	v_cvt_pk_bf16_f32 v56, v60, v61
	v_mov_b64_e32 v[60:61], v[150:151]
	v_pk_fma_f32 v[62:63], v[62:63], v[154:155], v[68:69] op_sel_hi:[1,1,0]
	s_nop 0
	v_cvt_pk_bf16_f32 v57, v62, v63
	v_cvt_pk_bf16_f32 v58, v58, v59
	v_cvt_pk_bf16_f32 v59, v74, v75
	s_cbranch_vccnz .LBB0_502
	v_mov_b32_e32 v125, v209
	v_lshl_add_u64 v[72:73], v[70:71], 0, v[124:125]
	s_mov_b64 s[46:47], 0
	v_mov_b64_e32 v[60:61], v[148:149]

; __device__ __forceinline__ unsigned pk2(float lo, float hi) { unsigned r; asm volatile("v_cvt_pk_bf16_f32 %0, %1, %2" : "=v"(r) : "v"(lo), "v"(hi)); return r; }
;     __device__ __forceinline__ void operator()(const f32x4 (&acc)[2][2][4][2], const Unit& u, int wr, int wc, int fr_, int fq_) const {
;     ...
;             for (int m = 0; m < 4; ++m) {
;                 const int ch = u.pm * 256 + ai * 128 + wr * 64 + m * 16 + fr, part = ch >> 9, c = ch & 511;
;                 const float swv = sw[(size_t)mb * NGU + ch];
; #pragma unroll
;                 for (int bj = 0; bj < 2; ++bj) {
;                     const f32x4 v0 = acc[ai][bj][m][0] * rs[bj][0] + swv, v1 = acc[ai][bj][m][1] * rs[bj][1] + swv;
;                     u32x4 w; w.x = pk2(v0[0], v0[1]); w.y = pk2(v0[2], v0[3]); w.z = pk2(v1[0], v1[1]); w.w = pk2(v1[2], v1[3]);
;                     bf16_t* dst;
;                     if (u.pn < 128) { const int b = u.pn >> 4, npos = (u.pn & 15) * 256 + bj * 128 + wc * 32 + 8 * fq; dst = FT + ((size_t)(b * 512 + c) * 8192 + part * 4096 + npos); }
;                     else { const int b = u.pn - 128, npos = bj * 128 + wc * 32 + 8 * fq; dst = FTC + ((size_t)(b * 512 + c) * 512 + part * 256 + npos); }
;                     *(u32x4*)dst = w;
.LBB0_504:
	v_mov_b32_e32 v69, v68
	global_store_dwordx4 v[72:73], v[56:59], off
	v_pk_fma_f32 v[52:53], v[52:53], v[132:133], v[68:69]
	v_lshlrev_b32_e32 v208, 1, v60
	v_mov_b32_e32 v56, v68
	v_mov_b32_e32 v57, v68
	v_pk_fma_f32 v[54:55], v[54:55], v[134:135], v[56:57]
	v_pk_fma_f32 v[56:57], v[50:51], v[130:131], v[56:57]
	v_pk_fma_f32 v[50:51], v[48:49], v[128:129], v[68:69]
	v_cvt_pk_bf16_f32 v48, v52, v53
	v_cndmask_b32_e64 v53, v71, v63, s[40:41]
	v_cndmask_b32_e64 v52, v70, v62, s[40:41]
	v_lshl_add_u64 v[52:53], v[52:53], 0, v[208:209]
	v_cvt_pk_bf16_f32 v49, v54, v55
	v_cvt_pk_bf16_f32 v50, v50, v51
	v_cvt_pk_bf16_f32 v51, v56, v57
	global_store_dwordx4 v[52:53], v[48:51], off offset:256
	s_nop 1
	v_mov_b32_e32 v48, v180
	s_movk_i32 s3, 0x1df
	v_bitop3_b32 v49, v64, s3, 16 bitop3:0xc8
	v_or_b32_e32 v208, s67, v49
	v_readlane_b32 s44, v252, 33
	v_lshlrev_b64 v[50:51], 10, v[208:209]
	v_readlane_b32 s45, v252, 34
	s_mov_b64 s[46:47], -1
	s_and_b64 vcc, exec, s[42:43]
	v_lshl_add_u64 v[50:51], s[44:45], 0, v[50:51]
	v_lshl_add_u64 v[50:51], s[80:81], 1, v[50:51]
	v_pk_fma_f32 v[44:45], v[44:45], v[152:153], v[48:49] op_sel_hi:[1,1,0]
	v_pk_fma_f32 v[54:55], v[42:43], v[158:159], v[48:49] op_sel_hi:[1,1,0]
	v_pk_fma_f32 v[42:43], v[40:41], v[156:157], v[48:49] op_sel_hi:[1,1,0]
	v_cvt_pk_bf16_f32 v40, v44, v45
	v_mov_b64_e32 v[44:45], v[150:151]
	v_pk_fma_f32 v[46:47], v[46:47], v[154:155], v[48:49] op_sel_hi:[1,1,0]
	s_nop 0
	v_cvt_pk_bf16_f32 v41, v46, v47
	v_cvt_pk_bf16_f32 v42, v42, v43
	v_cvt_pk_bf16_f32 v43, v54, v55
	s_cbranch_vccnz .LBB0_506
	v_mov_b32_e32 v125, v209
	v_lshl_add_u64 v[52:53], v[50:51], 0, v[124:125]
	s_mov_b64 s[46:47], 0
	v_mov_b64_e32 v[44:45], v[148:149]

; __device__ __forceinline__ unsigned pk2(float lo, float hi) { unsigned r; asm volatile("v_cvt_pk_bf16_f32 %0, %1, %2" : "=v"(r) : "v"(lo), "v"(hi)); return r; }
;     __device__ __forceinline__ void operator()(const f32x4 (&acc)[2][2][4][2], const Unit& u, int wr, int wc, int fr_, int fq_) const {
;     ...
;             for (int m = 0; m < 4; ++m) {
;                 const int ch = u.pm * 256 + ai * 128 + wr * 64 + m * 16 + fr, part = ch >> 9, c = ch & 511;
;                 const float swv = sw[(size_t)mb * NGU + ch];
; #pragma unroll
;                 for (int bj = 0; bj < 2; ++bj) {
;                     const f32x4 v0 = acc[ai][bj][m][0] * rs[bj][0] + swv, v1 = acc[ai][bj][m][1] * rs[bj][1] + swv;
;                     u32x4 w; w.x = pk2(v0[0], v0[1]); w.y = pk2(v0[2], v0[3]); w.z = pk2(v1[0], v1[1]); w.w = pk2(v1[2], v1[3]);
;                     bf16_t* dst;
;                     if (u.pn < 128) { const int b = u.pn >> 4, npos = (u.pn & 15) * 256 + bj * 128 + wc * 32 + 8 * fq; dst = FT + ((size_t)(b * 512 + c) * 8192 + part * 4096 + npos); }
;                     else { const int b = u.pn - 128, npos = bj * 128 + wc * 32 + 8 * fq; dst = FTC + ((size_t)(b * 512 + c) * 512 + part * 256 + npos); }
;                     *(u32x4*)dst = w;
.LBB0_508:
	v_mov_b32_e32 v49, v48
	global_store_dwordx4 v[52:53], v[40:43], off
	v_pk_fma_f32 v[36:37], v[36:37], v[132:133], v[48:49]
	v_lshlrev_b32_e32 v208, 1, v44
	v_mov_b32_e32 v40, v48
	v_mov_b32_e32 v41, v48
	v_pk_fma_f32 v[38:39], v[38:39], v[134:135], v[40:41]
	v_pk_fma_f32 v[40:41], v[34:35], v[130:131], v[40:41]
	v_pk_fma_f32 v[34:35], v[32:33], v[128:129], v[48:49]
	v_cvt_pk_bf16_f32 v32, v36, v37
	v_cndmask_b32_e64 v37, v51, v47, s[40:41]
	v_cndmask_b32_e64 v36, v50, v46, s[40:41]
	v_lshl_add_u64 v[36:37], v[36:37], 0, v[208:209]
	v_cvt_pk_bf16_f32 v33, v38, v39
	v_cvt_pk_bf16_f32 v34, v34, v35
	v_cvt_pk_bf16_f32 v35, v40, v41
	global_store_dwordx4 v[36:37], v[32:35], off offset:256
	s_nop 1
	v_mov_b32_e32 v32, v181
	s_movk_i32 s3, 0x1ef
	v_bitop3_b32 v33, v64, s3, 32 bitop3:0xc8
	v_or_b32_e32 v208, s67, v33
	v_readlane_b32 s44, v252, 33
	v_lshlrev_b64 v[34:35], 10, v[208:209]
	v_readlane_b32 s45, v252, 34
	s_mov_b64 s[46:47], -1
	s_and_b64 vcc, exec, s[42:43]
	v_lshl_add_u64 v[34:35], s[44:45], 0, v[34:35]
	v_lshl_add_u64 v[34:35], s[80:81], 1, v[34:35]
	v_pk_fma_f32 v[28:29], v[28:29], v[152:153], v[32:33] op_sel_hi:[1,1,0]
	v_pk_fma_f32 v[38:39], v[26:27], v[158:159], v[32:33] op_sel_hi:[1,1,0]
	v_pk_fma_f32 v[26:27], v[24:25], v[156:157], v[32:33] op_sel_hi:[1,1,0]
	v_cvt_pk_bf16_f32 v24, v28, v29
	v_mov_b64_e32 v[28:29], v[150:151]
	v_pk_fma_f32 v[30:31], v[30:31], v[154:155], v[32:33] op_sel_hi:[1,1,0]
	s_nop 0
	v_cvt_pk_bf16_f32 v25, v30, v31
	v_cvt_pk_bf16_f32 v26, v26, v27
	v_cvt_pk_bf16_f32 v27, v38, v39
	s_cbranch_vccnz .LBB0_510
	v_mov_b32_e32 v125, v209
	v_lshl_add_u64 v[36:37], v[34:35], 0, v[124:125]
	s_mov_b64 s[46:47], 0
	v_mov_b64_e32 v[28:29], v[148:149]

; __device__ __forceinline__ unsigned pk2(float lo, float hi) { unsigned r; asm volatile("v_cvt_pk_bf16_f32 %0, %1, %2" : "=v"(r) : "v"(lo), "v"(hi)); return r; }
;     __device__ __forceinline__ void operator()(const f32x4 (&acc)[2][2][4][2], const Unit& u, int wr, int wc, int fr_, int fq_) const {
;     ...
;             for (int m = 0; m < 4; ++m) {
;                 const int ch = u.pm * 256 + ai * 128 + wr * 64 + m * 16 + fr, part = ch >> 9, c = ch & 511;
;                 const float swv = sw[(size_t)mb * NGU + ch];
; #pragma unroll
;                 for (int bj = 0; bj < 2; ++bj) {
;                     const f32x4 v0 = acc[ai][bj][m][0] * rs[bj][0] + swv, v1 = acc[ai][bj][m][1] * rs[bj][1] + swv;
;                     u32x4 w; w.x = pk2(v0[0], v0[1]); w.y = pk2(v0[2], v0[3]); w.z = pk2(v1[0], v1[1]); w.w = pk2(v1[2], v1[3]);
;                     bf16_t* dst;
;                     if (u.pn < 128) { const int b = u.pn >> 4, npos = (u.pn & 15) * 256 + bj * 128 + wc * 32 + 8 * fq; dst = FT + ((size_t)(b * 512 + c) * 8192 + part * 4096 + npos); }
;                     else { const int b = u.pn - 128, npos = bj * 128 + wc * 32 + 8 * fq; dst = FTC + ((size_t)(b * 512 + c) * 512 + part * 256 + npos); }
;                     *(u32x4*)dst = w;
.LBB0_512:
	v_mov_b32_e32 v33, v32
	global_store_dwordx4 v[36:37], v[24:27], off
	v_pk_fma_f32 v[20:21], v[20:21], v[132:133], v[32:33]
	v_lshlrev_b32_e32 v208, 1, v28
	v_mov_b32_e32 v24, v32
	v_mov_b32_e32 v25, v32
	v_pk_fma_f32 v[22:23], v[22:23], v[134:135], v[24:25]
	v_pk_fma_f32 v[24:25], v[18:19], v[130:131], v[24:25]
	v_pk_fma_f32 v[18:19], v[16:17], v[128:129], v[32:33]
	v_cvt_pk_bf16_f32 v16, v20, v21
	v_cndmask_b32_e64 v21, v35, v31, s[40:41]
	v_cndmask_b32_e64 v20, v34, v30, s[40:41]
	v_lshl_add_u64 v[20:21], v[20:21], 0, v[208:209]
	v_cvt_pk_bf16_f32 v17, v22, v23
	v_cvt_pk_bf16_f32 v18, v18, v19
	v_cvt_pk_bf16_f32 v19, v24, v25
	global_store_dwordx4 v[20:21], v[16:19], off offset:256
	s_nop 1
	v_mov_b32_e32 v16, v182
	s_and_b64 vcc, exec, s[42:43]
	v_bitop3_b32 v17, v64, s6, 48 bitop3:0xc8
	v_or_b32_e32 v208, s67, v17
	v_readlane_b32 s42, v252, 33
	v_lshlrev_b64 v[18:19], 10, v[208:209]
	v_readlane_b32 s43, v252, 34
	s_mov_b64 s[46:47], -1
	v_pk_fma_f32 v[12:13], v[12:13], v[152:153], v[16:17] op_sel_hi:[1,1,0]
	v_pk_fma_f32 v[20:21], v[10:11], v[158:159], v[16:17] op_sel_hi:[1,1,0]
	v_pk_fma_f32 v[10:11], v[8:9], v[156:157], v[16:17] op_sel_hi:[1,1,0]
	v_cvt_pk_bf16_f32 v8, v12, v13
	v_lshl_add_u64 v[12:13], s[42:43], 0, v[18:19]
	v_lshl_add_u64 v[12:13], s[80:81], 1, v[12:13]
	v_pk_fma_f32 v[14:15], v[14:15], v[154:155], v[16:17] op_sel_hi:[1,1,0]
	s_nop 0
	v_cvt_pk_bf16_f32 v9, v14, v15
	v_cvt_pk_bf16_f32 v10, v10, v11
	v_cvt_pk_bf16_f32 v11, v20, v21
	s_cbranch_vccnz .LBB0_514
	v_mov_b32_e32 v125, v209
	v_lshl_add_u64 v[18:19], v[12:13], 0, v[124:125]
	s_mov_b64 s[46:47], 0
	v_mov_b64_e32 v[150:151], v[148:149]
